# plus: dead zero-initialisation of the 256 row_ror DPP destinations in the up-projection epilogue replaced by s_nop
# speedup vs baseline: 1.0090x; 1.0090x over previous
; __device__ __forceinline__ unsigned cvt_pk_bf16(float lo, float hi) { unsigned r; asm volatile("v_cvt_pk_bf16_f32 %0, %1, %2" : "=v"(r) : "v"(lo), "v"(hi)); return r; }
; __device__ __forceinline__ f32x4 gelu4(f32x4 v) { return (f32x4){gelu_t(v[0]), gelu_t(v[1]), gelu_t(v[2]), gelu_t(v[3])}; }
; template <int CTRL> __device__ __forceinline__ f32x4 dpp4(f32x4 v) { return (f32x4){dpp_f<CTRL>(v[0]), dpp_f<CTRL>(v[1]), dpp_f<CTRL>(v[2]), dpp_f<CTRL>(v[3])}; }
;     __device__ __forceinline__ void operator()(const f32x4 (&acc)[2][2][4][2], const Unit& u, int wr, int wc, int fr, int fq) const {
;     ...
; #pragma unroll
;             for (int n = 0; n < 2; ++n) {
;                 const int c = cgl + 4 * n;
;                 const f32x4 wg0 = *(const f32x4*)(bias + c), wg1 = *(const f32x4*)(bias + NUPc + c), wg2 = *(const f32x4*)(bias + 2 * NUPc + c), bg = *(const f32x4*)(xin + c);
;                 const f32x4 wv0 = *(const f32x4*)(bias + DFFc + c), wv1 = *(const f32x4*)(bias + NUPc + DFFc + c), wv2 = *(const f32x4*)(bias + 2 * NUPc + DFFc + c), bv = *(const f32x4*)(xin + DFFc + c);
; #pragma unroll
;                 for (int ai = 0; ai < 2; ++ai) {
;                     f32x4 pg1 = (f32x4){0.f, 0.f, 0.f, 0.f}, pg2 = pg1, pv1 = pg1, pv2 = pg1;
; #pragma unroll
;                     for (int m = 0; m < 4; ++m) {
;                         const f32x4 g = acc[ai][0][m][n] * rs[ai][m], v = acc[ai][1][m][n] * rs[ai][m];
;                         const f32x4 g1 = dpp4<0x121>(g), g2 = dpp4<0x122>(g), v1 = dpp4<0x121>(v), v2 = dpp4<0x122>(v);
;                         const f32x4 gp1 = (fr >= 1) ? g1 : pg1, gp2 = (fr >= 2) ? g2 : pg2, vp1 = (fr >= 1) ? v1 : pv1, vp2 = (fr >= 2) ? v2 : pv2;
;                         const f32x4 cgt = bg + wg0 * g + wg1 * gp1 + wg2 * gp2, cvl = bv + wv0 * v + wv1 * vp1 + wv2 * vp2;
;                         const f32x4 o = gelu4(cgt) * cvl;
;                         typedef unsigned u32x2e __attribute__((ext_vector_type(2)));
;                         u32x2e w; w.x = cvt_pk_bf16(o[0], o[1]); w.y = cvt_pk_bf16(o[2], o[3]);
;                         if (!(m == 0 && fr < 2)) *(u32x2e*)((bf16_t*)O + (size_t)(row0 + ai * HALF + m * 16) * DFFc + c) = w;
;                         pg1 = g1; pg2 = g2; pv1 = v1; pv2 = v2;
.LBB0_54:
	s_or_b64 exec, exec, s[48:49]
	v_lshl_or_b32 v180, s65, 7, v216
	v_ashrrev_i32_e32 v181, 31, v180
	v_lshlrev_b64 v[220:221], 2, v[180:181]
	v_lshl_add_u64 v[192:193], s[18:19], 0, v[220:221]
	v_lshl_add_u64 v[190:191], s[20:21], 0, v[220:221]
	v_lshl_add_u64 v[114:115], s[38:39], 0, v[220:221]
	global_load_dwordx4 v[110:113], v[192:193], off
	global_load_dwordx4 v[122:125], v[190:191], off
	global_load_dwordx4 v[118:121], v[114:115], off
	v_lshl_add_u64 v[114:115], s[26:27], 0, v[220:221]
	global_load_dwordx4 v[130:133], v[114:115], off
	v_lshl_add_u64 v[126:127], s[28:29], 0, v[220:221]
	global_load_dwordx4 v[126:129], v[126:127], off
	v_lshl_add_u64 v[106:107], s[30:31], 0, v[220:221]
	global_load_dwordx4 v[106:109], v[106:107], off
	v_lshl_add_u64 v[114:115], s[34:35], 0, v[220:221]
	global_load_dwordx4 v[114:117], v[114:115], off
	v_pk_mul_f32 v[236:237], v[134:135], v[188:189] op_sel_hi:[1,0]
	v_lshl_add_u64 v[134:135], s[36:37], 0, v[220:221]
	v_pk_mul_f32 v[234:235], v[136:137], v[188:189] op_sel_hi:[1,0]
	global_load_dwordx4 v[134:137], v[134:135], off
	v_pk_mul_f32 v[232:233], v[156:157], v[188:189] op_sel_hi:[1,0]
	v_pk_mul_f32 v[154:155], v[154:155], v[188:189] op_sel_hi:[1,0]
	s_nop 0
	s_nop 0
	s_nop 0
	s_nop 0
	v_mov_b32_dpp v157, v154 row_ror:1 row_mask:0xf bank_mask:0xf
	v_mov_b32_dpp v189, v155 row_ror:1 row_mask:0xf bank_mask:0xf
	v_mov_b32_dpp v219, v154 row_ror:2 row_mask:0xf bank_mask:0xf
	v_mov_b32_dpp v222, v155 row_ror:2 row_mask:0xf bank_mask:0xf
	v_cndmask_b32_e64 v241, v189, 0, s[6:7]
	v_cndmask_b32_e64 v240, v157, 0, s[6:7]
	v_cndmask_b32_e64 v245, 0, v222, s[10:11]
	v_cndmask_b32_e64 v244, 0, v219, s[10:11]
	s_nop 0
	s_nop 0
	s_nop 0
	s_nop 0
	v_mov_b32_dpp v218, v232 row_ror:1 row_mask:0xf bank_mask:0xf
	v_mov_b32_dpp v221, v233 row_ror:1 row_mask:0xf bank_mask:0xf
	v_mov_b32_dpp v220, v232 row_ror:2 row_mask:0xf bank_mask:0xf
	v_mov_b32_dpp v224, v233 row_ror:2 row_mask:0xf bank_mask:0xf
	v_cndmask_b32_e64 v239, v221, 0, s[6:7]
	v_cndmask_b32_e64 v238, v218, 0, s[6:7]
	v_cndmask_b32_e64 v243, 0, v224, s[10:11]
	v_cndmask_b32_e64 v242, 0, v220, s[10:11]
	s_nop 0
	s_nop 0
	s_nop 0
	s_nop 0
	s_nop 0
	s_nop 0
	v_mov_b32_dpp v223, v236 row_ror:1 row_mask:0xf bank_mask:0xf
	v_mov_b32_dpp v227, v237 row_ror:1 row_mask:0xf bank_mask:0xf
	s_nop 0
	s_nop 0
	v_mov_b32_dpp v225, v234 row_ror:1 row_mask:0xf bank_mask:0xf
	v_mov_b32_dpp v228, v235 row_ror:1 row_mask:0xf bank_mask:0xf
	v_mov_b32_dpp v226, v236 row_ror:2 row_mask:0xf bank_mask:0xf
	v_mov_b32_dpp v229, v237 row_ror:2 row_mask:0xf bank_mask:0xf
	v_cndmask_b32_e64 v249, v227, 0, s[6:7]
	v_cndmask_b32_e64 v248, v223, 0, s[6:7]
	v_mov_b32_dpp v230, v234 row_ror:2 row_mask:0xf bank_mask:0xf
	v_mov_b32_dpp v231, v235 row_ror:2 row_mask:0xf bank_mask:0xf
	v_cndmask_b32_e64 v247, v228, 0, s[6:7]
	v_cndmask_b32_e64 v246, v225, 0, s[6:7]
	v_cndmask_b32_e64 v201, 0, v229, s[10:11]
	v_cndmask_b32_e64 v200, 0, v226, s[10:11]
	v_cndmask_b32_e64 v251, 0, v231, s[10:11]
	v_cndmask_b32_e64 v250, 0, v230, s[10:11]
	s_waitcnt vmcnt(6)
	v_pk_fma_f32 v[154:155], v[154:155], v[110:111], v[122:123]
	v_pk_fma_f32 v[232:233], v[232:233], v[112:113], v[124:125]
	s_waitcnt vmcnt(4)
	v_pk_fma_f32 v[154:155], v[130:131], v[240:241], v[154:155]
	v_pk_fma_f32 v[232:233], v[132:133], v[238:239], v[232:233]
	s_waitcnt vmcnt(3)
	v_pk_fma_f32 v[154:155], v[126:127], v[244:245], v[154:155]
	v_pk_fma_f32 v[232:233], v[128:129], v[242:243], v[232:233]
	v_mul_f32_e32 v156, v154, v154
	v_fmamk_f32 v156, v156, 0xbdd2d3e8, v196
	v_mul_f32_e32 v156, v154, v156
	v_exp_f32_e32 v156, v156
	v_mul_f32_e32 v238, v155, v155
	v_mul_f32_e32 v239, v232, v232
	v_fmamk_f32 v238, v238, 0xbdd2d3e8, v196
	v_mul_f32_e32 v240, v233, v233
	v_fmamk_f32 v239, v239, 0xbdd2d3e8, v196
	v_mul_f32_e32 v238, v155, v238
	v_add_f32_e32 v156, 1.0, v156
	v_mul_f32_e32 v239, v232, v239
	v_exp_f32_e32 v241, v238
	v_rcp_f32_e32 v238, v156
	v_fmamk_f32 v156, v240, 0xbdd2d3e8, v196
	v_exp_f32_e32 v239, v239
	v_mul_f32_e32 v156, v233, v156
	v_exp_f32_e32 v156, v156
	v_add_f32_e32 v242, 1.0, v241
	v_add_f32_e32 v239, 1.0, v239
	v_rcp_f32_e32 v240, v239
	v_add_f32_e32 v156, 1.0, v156
	v_rcp_f32_e32 v239, v242
	v_rcp_f32_e32 v241, v156
	s_waitcnt vmcnt(2)
	v_pk_fma_f32 v[236:237], v[236:237], v[106:107], v[118:119]
	v_pk_fma_f32 v[234:235], v[234:235], v[108:109], v[120:121]
	s_waitcnt vmcnt(1)
	v_pk_fma_f32 v[236:237], v[114:115], v[248:249], v[236:237]
	v_pk_fma_f32 v[234:235], v[116:117], v[246:247], v[234:235]
	s_waitcnt vmcnt(0)
	v_pk_fma_f32 v[200:201], v[134:135], v[200:201], v[236:237]
	v_pk_mul_f32 v[154:155], v[154:155], v[238:239]
	v_pk_fma_f32 v[234:235], v[136:137], v[250:251], v[234:235]
	v_pk_mul_f32 v[232:233], v[232:233], v[240:241]
	v_pk_mul_f32 v[154:155], v[200:201], v[154:155]
	v_pk_mul_f32 v[232:233], v[234:235], v[232:233]
	v_cvt_pk_bf16_f32 v154, v154, v155
	s_nop 0
	v_cvt_pk_bf16_f32 v155, v232, v233
	s_and_saveexec_b64 s[48:49], s[10:11]
	s_cbranch_execz .LBB0_56
	v_mov_b64_e32 v[200:201], s[68:69]
	v_mad_i64_i32 v[200:201], s[50:51], v186, s76, v[200:201]
	v_lshl_add_u64 v[200:201], v[180:181], 1, v[200:201]
	global_store_dwordx2 v[200:201], v[154:155], off
; __device__ __forceinline__ unsigned cvt_pk_bf16(float lo, float hi) { unsigned r; asm volatile("v_cvt_pk_bf16_f32 %0, %1, %2" : "=v"(r) : "v"(lo), "v"(hi)); return r; }
; __device__ __forceinline__ f32x4 gelu4(f32x4 v) { return (f32x4){gelu_t(v[0]), gelu_t(v[1]), gelu_t(v[2]), gelu_t(v[3])}; }
; template <int CTRL> __device__ __forceinline__ f32x4 dpp4(f32x4 v) { return (f32x4){dpp_f<CTRL>(v[0]), dpp_f<CTRL>(v[1]), dpp_f<CTRL>(v[2]), dpp_f<CTRL>(v[3])}; }
;     __device__ __forceinline__ void operator()(const f32x4 (&acc)[2][2][4][2], const Unit& u, int wr, int wc, int fr, int fq) const {
;     ...
; #pragma unroll
;             for (int n = 0; n < 2; ++n) {
;                 const int c = cgl + 4 * n;
;                 const f32x4 wg0 = *(const f32x4*)(bias + c), wg1 = *(const f32x4*)(bias + NUPc + c), wg2 = *(const f32x4*)(bias + 2 * NUPc + c), bg = *(const f32x4*)(xin + c);
;                 const f32x4 wv0 = *(const f32x4*)(bias + DFFc + c), wv1 = *(const f32x4*)(bias + NUPc + DFFc + c), wv2 = *(const f32x4*)(bias + 2 * NUPc + DFFc + c), bv = *(const f32x4*)(xin + DFFc + c);
; #pragma unroll
;                 for (int ai = 0; ai < 2; ++ai) {
;                     f32x4 pg1 = (f32x4){0.f, 0.f, 0.f, 0.f}, pg2 = pg1, pv1 = pg1, pv2 = pg1;
; #pragma unroll
;                     for (int m = 0; m < 4; ++m) {
;                         const f32x4 g = acc[ai][0][m][n] * rs[ai][m], v = acc[ai][1][m][n] * rs[ai][m];
;                         const f32x4 g1 = dpp4<0x121>(g), g2 = dpp4<0x122>(g), v1 = dpp4<0x121>(v), v2 = dpp4<0x122>(v);
;                         const f32x4 gp1 = (fr >= 1) ? g1 : pg1, gp2 = (fr >= 2) ? g2 : pg2, vp1 = (fr >= 1) ? v1 : pv1, vp2 = (fr >= 2) ? v2 : pv2;
;                         const f32x4 cgt = bg + wg0 * g + wg1 * gp1 + wg2 * gp2, cvl = bv + wv0 * v + wv1 * vp1 + wv2 * vp2;
;                         const f32x4 o = gelu4(cgt) * cvl;
;                         typedef unsigned u32x2e __attribute__((ext_vector_type(2)));
;                         u32x2e w; w.x = cvt_pk_bf16(o[0], o[1]); w.y = cvt_pk_bf16(o[2], o[3]);
;                         if (!(m == 0 && fr < 2)) *(u32x2e*)((bf16_t*)O + (size_t)(row0 + ai * HALF + m * 16) * DFFc + c) = w;
;                         pg1 = g1; pg2 = g2; pv1 = v1; pv2 = v2;
.LBB0_56:
	s_or_b64 exec, exec, s[48:49]
	v_fmamk_f32 v154, v187, 0x3a000000, v197
	v_cmp_gt_f32_e32 vcc, s67, v154
	v_mul_f32_e32 v155, 0x4b800000, v154
	s_nop 0
	v_cndmask_b32_e32 v154, v154, v155, vcc
	v_rsq_f32_e32 v154, v154
	s_nop 0
	s_nop 0
	s_nop 0
	v_mul_f32_e32 v155, 0x45800000, v154
	v_cndmask_b32_e32 v156, v154, v155, vcc
	v_pk_mul_f32 v[150:151], v[150:151], v[156:157] op_sel_hi:[1,0]
	v_pk_mul_f32 v[152:153], v[152:153], v[156:157] op_sel_hi:[1,0]
	v_pk_mul_f32 v[148:149], v[148:149], v[156:157] op_sel_hi:[1,0]
	v_mov_b32_dpp v237, v150 row_ror:1 row_mask:0xf bank_mask:0xf
	v_mov_b32_dpp v238, v151 row_ror:1 row_mask:0xf bank_mask:0xf
	v_mov_b32_dpp v241, v150 row_ror:2 row_mask:0xf bank_mask:0xf
	v_mov_b32_dpp v242, v151 row_ror:2 row_mask:0xf bank_mask:0xf
	v_cndmask_b32_e64 v233, v238, v189, s[6:7]
	v_cndmask_b32_e64 v232, v237, v157, s[6:7]
	v_pk_fma_f32 v[150:151], v[150:151], v[110:111], v[122:123]
	v_cndmask_b32_e64 v235, v222, v242, s[10:11]
	v_cndmask_b32_e64 v234, v219, v241, s[10:11]
	v_pk_fma_f32 v[150:151], v[130:131], v[232:233], v[150:151]
	v_pk_mul_f32 v[146:147], v[146:147], v[156:157] op_sel_hi:[1,0]
	v_pk_fma_f32 v[150:151], v[126:127], v[234:235], v[150:151]
	s_nop 0
	v_mul_f32_e32 v157, v150, v150
	v_fmamk_f32 v157, v157, 0xbdd2d3e8, v196
	v_mul_f32_e32 v157, v150, v157
	v_exp_f32_e32 v157, v157
	s_nop 0
	v_mov_b32_dpp v239, v152 row_ror:1 row_mask:0xf bank_mask:0xf
	s_nop 0
	v_mov_b32_dpp v240, v153 row_ror:1 row_mask:0xf bank_mask:0xf
	s_nop 0
	v_mov_b32_dpp v243, v152 row_ror:2 row_mask:0xf bank_mask:0xf
	v_cndmask_b32_e64 v201, v240, v221, s[6:7]
	v_mov_b32_dpp v244, v153 row_ror:2 row_mask:0xf bank_mask:0xf
	v_cndmask_b32_e64 v200, v239, v218, s[6:7]
	v_pk_fma_f32 v[152:153], v[152:153], v[112:113], v[124:125]
	v_add_f32_e32 v157, 1.0, v157
	v_pk_fma_f32 v[152:153], v[132:133], v[200:201], v[152:153]
	v_rcp_f32_e32 v200, v157
	v_mul_f32_e32 v157, v151, v151
	v_fmamk_f32 v157, v157, 0xbdd2d3e8, v196
	v_mul_f32_e32 v157, v151, v157
	v_exp_f32_e32 v157, v157
	v_cndmask_b32_e64 v219, v224, v244, s[10:11]
	v_cndmask_b32_e64 v218, v220, v243, s[10:11]
	v_pk_fma_f32 v[152:153], v[128:129], v[218:219], v[152:153]
	v_add_f32_e32 v157, 1.0, v157
	v_rcp_f32_e32 v201, v157
	v_mul_f32_e32 v157, v152, v152
	v_fmamk_f32 v157, v157, 0xbdd2d3e8, v196
	v_mul_f32_e32 v157, v152, v157
	v_exp_f32_e32 v157, v157
	v_fmamk_f32 v154, v179, 0x3a000000, v197
	v_cmp_gt_f32_e32 vcc, s67, v154
	v_mul_f32_e32 v155, 0x4b800000, v154
	v_add_f32_e32 v157, 1.0, v157
	v_rcp_f32_e32 v218, v157
	v_mul_f32_e32 v157, v153, v153
	v_fmamk_f32 v157, v157, 0xbdd2d3e8, v196
	v_mul_f32_e32 v157, v153, v157
	v_exp_f32_e32 v157, v157
	v_cndmask_b32_e32 v154, v154, v155, vcc
	v_rsq_f32_e32 v154, v154
	s_nop 0
	v_add_f32_e32 v157, 1.0, v157
	s_nop 0
	s_nop 0
	s_nop 0
	v_rcp_f32_e32 v219, v157
	v_mov_b32_dpp v245, v146 row_ror:1 row_mask:0xf bank_mask:0xf
	v_mov_b32_dpp v246, v147 row_ror:1 row_mask:0xf bank_mask:0xf
	v_mov_b32_dpp v247, v148 row_ror:1 row_mask:0xf bank_mask:0xf
	v_mov_b32_dpp v248, v149 row_ror:1 row_mask:0xf bank_mask:0xf
	s_nop 0
	s_nop 0
	s_nop 0
	s_nop 0
	v_mul_f32_e32 v155, 0x45800000, v154
	v_mov_b32_dpp v249, v146 row_ror:2 row_mask:0xf bank_mask:0xf
	v_mov_b32_dpp v250, v147 row_ror:2 row_mask:0xf bank_mask:0xf
	v_mov_b32_dpp v251, v148 row_ror:2 row_mask:0xf bank_mask:0xf
	v_mov_b32_dpp v211, v149 row_ror:2 row_mask:0xf bank_mask:0xf
	v_cndmask_b32_e64 v221, v246, v227, s[6:7]
	v_cndmask_b32_e64 v220, v245, v223, s[6:7]
	v_cndmask_b32_e64 v223, v248, v228, s[6:7]
	v_cndmask_b32_e64 v222, v247, v225, s[6:7]
	v_pk_fma_f32 v[146:147], v[146:147], v[106:107], v[118:119]
	v_pk_fma_f32 v[148:149], v[148:149], v[108:109], v[120:121]
	v_cndmask_b32_e32 v154, v154, v155, vcc
	v_or_b32_e32 v155, 48, v186
	v_cndmask_b32_e64 v225, v231, v211, s[10:11]
	v_cndmask_b32_e64 v224, v230, v251, s[10:11]
	v_cndmask_b32_e64 v227, v229, v250, s[10:11]
	v_cndmask_b32_e64 v226, v226, v249, s[10:11]
	v_pk_fma_f32 v[148:149], v[116:117], v[222:223], v[148:149]
	v_pk_fma_f32 v[146:147], v[114:115], v[220:221], v[146:147]
	v_pk_fma_f32 v[148:149], v[136:137], v[224:225], v[148:149]
	v_pk_fma_f32 v[146:147], v[134:135], v[226:227], v[146:147]
	v_pk_mul_f32 v[150:151], v[150:151], v[200:201]
	v_pk_mul_f32 v[152:153], v[152:153], v[218:219]
	v_pk_mul_f32 v[142:143], v[142:143], v[154:155] op_sel_hi:[1,0]
	s_nop 0
	s_nop 0
	v_or_b32_e32 v236, 16, v186
	v_pk_mul_f32 v[148:149], v[148:149], v[152:153]
	v_pk_mul_f32 v[146:147], v[146:147], v[150:151]
	v_mov_b64_e32 v[150:151], s[68:69]
	s_movk_i32 s41, 0x2c00
	v_mov_b32_dpp v157, v142 row_ror:1 row_mask:0xf bank_mask:0xf
	v_mov_b32_dpp v189, v143 row_ror:1 row_mask:0xf bank_mask:0xf
	s_nop 0
	s_nop 0
	v_cvt_pk_bf16_f32 v152, v146, v147
	v_cvt_pk_bf16_f32 v153, v148, v149
	v_mad_i64_i32 v[146:147], s[48:49], v236, s41, v[150:151]
	v_lshlrev_b64 v[148:149], 1, v[180:181]
	v_pk_mul_f32 v[144:145], v[144:145], v[154:155] op_sel_hi:[1,0]
	s_nop 0
	s_nop 0
	v_mov_b32_dpp v232, v142 row_ror:2 row_mask:0xf bank_mask:0xf
	v_mov_b32_dpp v233, v143 row_ror:2 row_mask:0xf bank_mask:0xf
	v_cndmask_b32_e64 v201, v189, v238, s[6:7]
	v_cndmask_b32_e64 v200, v157, v237, s[6:7]
	v_pk_fma_f32 v[142:143], v[142:143], v[110:111], v[122:123]
	v_lshl_add_u64 v[146:147], v[146:147], 0, v[148:149]
	v_mov_b32_dpp v230, v144 row_ror:1 row_mask:0xf bank_mask:0xf
	v_mov_b32_dpp v231, v145 row_ror:1 row_mask:0xf bank_mask:0xf
	s_nop 0
	s_nop 0
	v_cndmask_b32_e64 v219, v242, v233, s[10:11]
	v_cndmask_b32_e64 v218, v241, v232, s[10:11]
	v_pk_fma_f32 v[142:143], v[130:131], v[200:201], v[142:143]
	global_store_dwordx2 v[146:147], v[152:153], off
; __device__ __forceinline__ unsigned cvt_pk_bf16(float lo, float hi) { unsigned r; asm volatile("v_cvt_pk_bf16_f32 %0, %1, %2" : "=v"(r) : "v"(lo), "v"(hi)); return r; }
; __device__ __forceinline__ f32x4 gelu4(f32x4 v) { return (f32x4){gelu_t(v[0]), gelu_t(v[1]), gelu_t(v[2]), gelu_t(v[3])}; }
; template <int CTRL> __device__ __forceinline__ f32x4 dpp4(f32x4 v) { return (f32x4){dpp_f<CTRL>(v[0]), dpp_f<CTRL>(v[1]), dpp_f<CTRL>(v[2]), dpp_f<CTRL>(v[3])}; }
;     __device__ __forceinline__ void operator()(const f32x4 (&acc)[2][2][4][2], const Unit& u, int wr, int wc, int fr, int fq) const {
;     ...
; #pragma unroll
;             for (int n = 0; n < 2; ++n) {
;                 const int c = cgl + 4 * n;
;                 const f32x4 wg0 = *(const f32x4*)(bias + c), wg1 = *(const f32x4*)(bias + NUPc + c), wg2 = *(const f32x4*)(bias + 2 * NUPc + c), bg = *(const f32x4*)(xin + c);
;                 const f32x4 wv0 = *(const f32x4*)(bias + DFFc + c), wv1 = *(const f32x4*)(bias + NUPc + DFFc + c), wv2 = *(const f32x4*)(bias + 2 * NUPc + DFFc + c), bv = *(const f32x4*)(xin + DFFc + c);
; #pragma unroll
;                 for (int ai = 0; ai < 2; ++ai) {
;                     f32x4 pg1 = (f32x4){0.f, 0.f, 0.f, 0.f}, pg2 = pg1, pv1 = pg1, pv2 = pg1;
; #pragma unroll
;                     for (int m = 0; m < 4; ++m) {
;                         const f32x4 g = acc[ai][0][m][n] * rs[ai][m], v = acc[ai][1][m][n] * rs[ai][m];
;                         const f32x4 g1 = dpp4<0x121>(g), g2 = dpp4<0x122>(g), v1 = dpp4<0x121>(v), v2 = dpp4<0x122>(v);
;                         const f32x4 gp1 = (fr >= 1) ? g1 : pg1, gp2 = (fr >= 2) ? g2 : pg2, vp1 = (fr >= 1) ? v1 : pv1, vp2 = (fr >= 2) ? v2 : pv2;
;                         const f32x4 cgt = bg + wg0 * g + wg1 * gp1 + wg2 * gp2, cvl = bv + wv0 * v + wv1 * vp1 + wv2 * vp2;
;                         const f32x4 o = gelu4(cgt) * cvl;
;                         typedef unsigned u32x2e __attribute__((ext_vector_type(2)));
;                         u32x2e w; w.x = cvt_pk_bf16(o[0], o[1]); w.y = cvt_pk_bf16(o[2], o[3]);
;                         if (!(m == 0 && fr < 2)) *(u32x2e*)((bf16_t*)O + (size_t)(row0 + ai * HALF + m * 16) * DFFc + c) = w;
;                         pg1 = g1; pg2 = g2; pv1 = v1; pv2 = v2;
	v_mov_b32_dpp v234, v144 row_ror:2 row_mask:0xf bank_mask:0xf
	v_mov_b32_dpp v235, v145 row_ror:2 row_mask:0xf bank_mask:0xf
	v_cndmask_b32_e64 v153, v231, v240, s[6:7]
	v_cndmask_b32_e64 v152, v230, v239, s[6:7]
	v_pk_fma_f32 v[144:145], v[144:145], v[112:113], v[124:125]
	v_pk_fma_f32 v[142:143], v[126:127], v[218:219], v[142:143]
	v_cndmask_b32_e64 v221, v244, v235, s[10:11]
	v_cndmask_b32_e64 v220, v243, v234, s[10:11]
	v_pk_fma_f32 v[144:145], v[132:133], v[152:153], v[144:145]
	v_mul_f32_e32 v152, v142, v142
	v_mul_f32_e32 v153, v143, v143
	v_pk_fma_f32 v[144:145], v[128:129], v[220:221], v[144:145]
	v_fmamk_f32 v152, v152, 0xbdd2d3e8, v196
	v_fmamk_f32 v153, v153, 0xbdd2d3e8, v196
	v_mul_f32_e32 v152, v142, v152
	v_mul_f32_e32 v153, v143, v153
	v_mul_f32_e32 v200, v144, v144
	v_mul_f32_e32 v201, v145, v145
	v_exp_f32_e32 v152, v152
	v_exp_f32_e32 v153, v153
	v_fmamk_f32 v200, v200, 0xbdd2d3e8, v196
	v_fmamk_f32 v201, v201, 0xbdd2d3e8, v196
	v_mul_f32_e32 v200, v144, v200
	v_mul_f32_e32 v201, v145, v201
	v_exp_f32_e32 v200, v200
	v_exp_f32_e32 v201, v201
	v_add_f32_e32 v152, 1.0, v152
	v_add_f32_e32 v153, 1.0, v153
	v_pk_mul_f32 v[138:139], v[138:139], v[154:155] op_sel_hi:[1,0]
	s_nop 0
	s_nop 0
	v_rcp_f32_e32 v152, v152
	v_rcp_f32_e32 v153, v153
	v_mov_b32_dpp v236, v138 row_ror:1 row_mask:0xf bank_mask:0xf
	v_mov_b32_dpp v208, v139 row_ror:1 row_mask:0xf bank_mask:0xf
	s_nop 0
	s_nop 0
	v_add_f32_e32 v200, 1.0, v200
	v_add_f32_e32 v201, 1.0, v201
	v_pk_mul_f32 v[140:141], v[140:141], v[154:155] op_sel_hi:[1,0]
	s_nop 0
	s_nop 0
	v_mov_b32_dpp v207, v138 row_ror:2 row_mask:0xf bank_mask:0xf
	v_mov_b32_dpp v209, v139 row_ror:2 row_mask:0xf bank_mask:0xf
	v_cndmask_b32_e64 v223, v208, v246, s[6:7]
	v_cndmask_b32_e64 v222, v236, v245, s[6:7]
	v_pk_fma_f32 v[138:139], v[138:139], v[106:107], v[118:119]
	v_rcp_f32_e32 v200, v200
	v_rcp_f32_e32 v201, v201
	v_mov_b32_dpp v199, v140 row_ror:1 row_mask:0xf bank_mask:0xf
	v_mov_b32_dpp v205, v141 row_ror:1 row_mask:0xf bank_mask:0xf
	s_nop 0
	s_nop 0
	v_cndmask_b32_e64 v229, v250, v209, s[10:11]
	v_cndmask_b32_e64 v228, v249, v207, s[10:11]
	v_pk_fma_f32 v[138:139], v[114:115], v[222:223], v[138:139]
	v_mov_b32_dpp v210, v140 row_ror:2 row_mask:0xf bank_mask:0xf
	v_mov_b32_dpp v206, v141 row_ror:2 row_mask:0xf bank_mask:0xf
	v_cndmask_b32_e64 v225, v205, v248, s[6:7]
	v_cndmask_b32_e64 v224, v199, v247, s[6:7]
	v_pk_fma_f32 v[140:141], v[140:141], v[108:109], v[120:121]
	v_pk_fma_f32 v[138:139], v[134:135], v[228:229], v[138:139]
	v_pk_mul_f32 v[142:143], v[142:143], v[152:153]
	v_or_b32_e32 v187, 32, v186
	v_cndmask_b32_e64 v227, v211, v206, s[10:11]
	v_cndmask_b32_e64 v226, v251, v210, s[10:11]
	v_pk_fma_f32 v[140:141], v[116:117], v[224:225], v[140:141]
	v_pk_mul_f32 v[138:139], v[138:139], v[142:143]
	v_pk_fma_f32 v[140:141], v[136:137], v[226:227], v[140:141]
	v_pk_mul_f32 v[144:145], v[144:145], v[200:201]
	v_cvt_pk_bf16_f32 v142, v138, v139
	v_mad_i64_i32 v[138:139], s[48:49], v187, s41, v[150:151]
	v_pk_mul_f32 v[140:141], v[140:141], v[144:145]
	v_lshl_add_u64 v[138:139], v[138:139], 0, v[148:149]
	v_cvt_pk_bf16_f32 v143, v140, v141
	global_store_dwordx2 v[138:139], v[142:143], off
	v_pk_mul_f32 v[104:105], v[104:105], v[184:185] op_sel_hi:[1,0]
	v_pk_mul_f32 v[102:103], v[102:103], v[184:185] op_sel_hi:[1,0]
	s_nop 0
	s_nop 0
	s_nop 0
	s_nop 0
	v_mov_b32_dpp v142, v102 row_ror:1 row_mask:0xf bank_mask:0xf
	v_mov_b32_dpp v143, v103 row_ror:1 row_mask:0xf bank_mask:0xf
	v_mov_b32_dpp v140, v104 row_ror:1 row_mask:0xf bank_mask:0xf
	v_mov_b32_dpp v141, v105 row_ror:1 row_mask:0xf bank_mask:0xf
	s_nop 0
	s_nop 0
	s_nop 0
	s_nop 0
	v_mov_b32_dpp v144, v102 row_ror:2 row_mask:0xf bank_mask:0xf
	v_mov_b32_dpp v145, v103 row_ror:2 row_mask:0xf bank_mask:0xf
	v_mov_b32_dpp v152, v104 row_ror:2 row_mask:0xf bank_mask:0xf
	v_mov_b32_dpp v153, v105 row_ror:2 row_mask:0xf bank_mask:0xf
	v_cndmask_b32_e64 v141, v141, v231, s[6:7]
	v_cndmask_b32_e64 v140, v140, v230, s[6:7]
	v_cndmask_b32_e64 v143, v143, v189, s[6:7]
	v_cndmask_b32_e64 v142, v142, v157, s[6:7]
	v_pk_fma_f32 v[104:105], v[104:105], v[112:113], v[124:125]
	v_pk_fma_f32 v[102:103], v[102:103], v[110:111], v[122:123]
	v_cndmask_b32_e64 v145, v233, v145, s[10:11]
	v_cndmask_b32_e64 v144, v232, v144, s[10:11]
	v_cndmask_b32_e64 v153, v235, v153, s[10:11]
	v_cndmask_b32_e64 v152, v234, v152, s[10:11]
	v_pk_fma_f32 v[102:103], v[130:131], v[142:143], v[102:103]
	v_pk_fma_f32 v[104:105], v[132:133], v[140:141], v[104:105]
	v_pk_fma_f32 v[102:103], v[126:127], v[144:145], v[102:103]
	v_pk_fma_f32 v[104:105], v[128:129], v[152:153], v[104:105]
	v_mul_f32_e32 v140, v102, v102
	v_mul_f32_e32 v141, v103, v103
	v_mul_f32_e32 v142, v104, v104
	v_mul_f32_e32 v143, v105, v105
	v_fmamk_f32 v140, v140, 0xbdd2d3e8, v196
	v_fmamk_f32 v141, v141, 0xbdd2d3e8, v196
	v_fmamk_f32 v142, v142, 0xbdd2d3e8, v196
	v_fmamk_f32 v143, v143, 0xbdd2d3e8, v196
	v_mul_f32_e32 v140, v102, v140
	v_mul_f32_e32 v141, v103, v141
	v_mul_f32_e32 v142, v104, v142
	v_mul_f32_e32 v143, v105, v143
	v_exp_f32_e32 v140, v140
	v_exp_f32_e32 v141, v141
	v_exp_f32_e32 v142, v142
	v_exp_f32_e32 v143, v143
	v_add_f32_e32 v140, 1.0, v140
	v_add_f32_e32 v141, 1.0, v141
	v_add_f32_e32 v142, 1.0, v142
	v_add_f32_e32 v143, 1.0, v143
	v_pk_mul_f32 v[100:101], v[100:101], v[184:185] op_sel_hi:[1,0]
	v_pk_mul_f32 v[98:99], v[98:99], v[184:185] op_sel_hi:[1,0]
	s_nop 0
	s_nop 0
	s_nop 0
	s_nop 0
	v_rcp_f32_e32 v140, v140
	v_rcp_f32_e32 v141, v141
	v_rcp_f32_e32 v142, v142
	v_rcp_f32_e32 v143, v143
	v_mov_b32_dpp v187, v98 row_ror:1 row_mask:0xf bank_mask:0xf
; __device__ __forceinline__ unsigned cvt_pk_bf16(float lo, float hi) { unsigned r; asm volatile("v_cvt_pk_bf16_f32 %0, %1, %2" : "=v"(r) : "v"(lo), "v"(hi)); return r; }
; __device__ __forceinline__ f32x4 gelu4(f32x4 v) { return (f32x4){gelu_t(v[0]), gelu_t(v[1]), gelu_t(v[2]), gelu_t(v[3])}; }
; template <int CTRL> __device__ __forceinline__ f32x4 dpp4(f32x4 v) { return (f32x4){dpp_f<CTRL>(v[0]), dpp_f<CTRL>(v[1]), dpp_f<CTRL>(v[2]), dpp_f<CTRL>(v[3])}; }
;     __device__ __forceinline__ void operator()(const f32x4 (&acc)[2][2][4][2], const Unit& u, int wr, int wc, int fr, int fq) const {
;     ...
;                     for (int m = 0; m < 4; ++m) {
;                         const f32x4 g = acc[ai][0][m][n] * rs[ai][m], v = acc[ai][1][m][n] * rs[ai][m];
;                         const f32x4 g1 = dpp4<0x121>(g), g2 = dpp4<0x122>(g), v1 = dpp4<0x121>(v), v2 = dpp4<0x122>(v);
;                         const f32x4 gp1 = (fr >= 1) ? g1 : pg1, gp2 = (fr >= 2) ? g2 : pg2, vp1 = (fr >= 1) ? v1 : pv1, vp2 = (fr >= 2) ? v2 : pv2;
;                         const f32x4 cgt = bg + wg0 * g + wg1 * gp1 + wg2 * gp2, cvl = bv + wv0 * v + wv1 * vp1 + wv2 * vp2;
;                         const f32x4 o = gelu4(cgt) * cvl;
;                         typedef unsigned u32x2e __attribute__((ext_vector_type(2)));
;                         u32x2e w; w.x = cvt_pk_bf16(o[0], o[1]); w.y = cvt_pk_bf16(o[2], o[3]);
;                         if (!(m == 0 && fr < 2)) *(u32x2e*)((bf16_t*)O + (size_t)(row0 + ai * HALF + m * 16) * DFFc + c) = w;
;                         pg1 = g1; pg2 = g2; pv1 = v1; pv2 = v2;
	v_mov_b32_dpp v200, v99 row_ror:1 row_mask:0xf bank_mask:0xf
	v_mov_b32_dpp v211, v100 row_ror:1 row_mask:0xf bank_mask:0xf
	v_mov_b32_dpp v218, v101 row_ror:1 row_mask:0xf bank_mask:0xf
	s_nop 0
	s_nop 0
	s_nop 0
	s_nop 0
	v_mov_b32_dpp v222, v98 row_ror:2 row_mask:0xf bank_mask:0xf
	v_mov_b32_dpp v223, v99 row_ror:2 row_mask:0xf bank_mask:0xf
	v_mov_b32_dpp v220, v100 row_ror:2 row_mask:0xf bank_mask:0xf
	v_mov_b32_dpp v221, v101 row_ror:2 row_mask:0xf bank_mask:0xf
	v_cndmask_b32_e64 v201, v200, v208, s[6:7]
	v_cndmask_b32_e64 v200, v187, v236, s[6:7]
	v_cndmask_b32_e64 v219, v218, v205, s[6:7]
	v_cndmask_b32_e64 v218, v211, v199, s[6:7]
	v_pk_fma_f32 v[100:101], v[100:101], v[108:109], v[120:121]
	v_pk_fma_f32 v[98:99], v[98:99], v[106:107], v[118:119]
	v_cndmask_b32_e64 v221, v206, v221, s[10:11]
	v_cndmask_b32_e64 v220, v210, v220, s[10:11]
	v_cndmask_b32_e64 v223, v209, v223, s[10:11]
	v_cndmask_b32_e64 v222, v207, v222, s[10:11]
	v_pk_fma_f32 v[100:101], v[116:117], v[218:219], v[100:101]
	v_pk_fma_f32 v[98:99], v[114:115], v[200:201], v[98:99]
	v_pk_fma_f32 v[100:101], v[136:137], v[220:221], v[100:101]
	v_pk_fma_f32 v[98:99], v[134:135], v[222:223], v[98:99]
	v_pk_mul_f32 v[102:103], v[102:103], v[140:141]
	v_pk_mul_f32 v[104:105], v[104:105], v[142:143]
	v_pk_mul_f32 v[98:99], v[98:99], v[102:103]
	v_pk_mul_f32 v[100:101], v[100:101], v[104:105]
	v_cvt_pk_bf16_f32 v98, v98, v99
	v_pk_mul_f32 v[152:153], v[94:95], v[182:183] op_sel_hi:[1,0]
	v_cvt_pk_bf16_f32 v99, v100, v101
	v_mad_i64_i32 v[100:101], s[48:49], v155, s41, v[150:151]
	v_lshl_add_u64 v[100:101], v[100:101], 0, v[148:149]
	v_pk_mul_f32 v[200:201], v[92:93], v[182:183] op_sel_hi:[1,0]
	s_nop 0
	s_nop 0
	global_store_dwordx2 v[100:101], v[98:99], off
	v_mov_b32_dpp v92, v152 row_ror:1 row_mask:0xf bank_mask:0xf
	v_mov_b32_dpp v93, v153 row_ror:1 row_mask:0xf bank_mask:0xf
	s_nop 0
	s_nop 0
	v_cndmask_b32_e64 v221, v93, 0, s[6:7]
	v_mov_b32_dpp v95, v152 row_ror:2 row_mask:0xf bank_mask:0xf
	v_mov_b32_dpp v99, v153 row_ror:2 row_mask:0xf bank_mask:0xf
	v_cndmask_b32_e64 v220, v92, 0, s[6:7]
	v_pk_fma_f32 v[152:153], v[152:153], v[110:111], v[122:123]
	v_cndmask_b32_e64 v225, 0, v99, s[10:11]
	v_cndmask_b32_e64 v224, 0, v95, s[10:11]
	v_pk_fma_f32 v[152:153], v[130:131], v[220:221], v[152:153]
	v_pk_mul_f32 v[150:151], v[96:97], v[182:183] op_sel_hi:[1,0]
	v_pk_fma_f32 v[152:153], v[126:127], v[224:225], v[152:153]
	s_nop 0
	v_mul_f32_e32 v98, v152, v152
	v_fmamk_f32 v98, v98, 0xbdd2d3e8, v196
	v_mul_f32_e32 v98, v152, v98
	v_exp_f32_e32 v98, v98
	s_nop 0
	v_mov_b32_dpp v94, v150 row_ror:1 row_mask:0xf bank_mask:0xf
	s_nop 0
	v_mov_b32_dpp v97, v151 row_ror:1 row_mask:0xf bank_mask:0xf
	s_nop 0
	v_mov_b32_dpp v96, v150 row_ror:2 row_mask:0xf bank_mask:0xf
	v_cndmask_b32_e64 v219, v97, 0, s[6:7]
	v_mov_b32_dpp v104, v151 row_ror:2 row_mask:0xf bank_mask:0xf
	v_cndmask_b32_e64 v218, v94, 0, s[6:7]
	v_pk_fma_f32 v[150:151], v[150:151], v[112:113], v[124:125]
	v_add_f32_e32 v98, 1.0, v98
	v_pk_fma_f32 v[150:151], v[132:133], v[218:219], v[150:151]
	v_rcp_f32_e32 v218, v98
	v_mul_f32_e32 v98, v153, v153
	v_fmamk_f32 v98, v98, 0xbdd2d3e8, v196
	v_mul_f32_e32 v98, v153, v98
	v_exp_f32_e32 v98, v98
	v_cndmask_b32_e64 v223, 0, v104, s[10:11]
	v_cndmask_b32_e64 v222, 0, v96, s[10:11]
	v_pk_fma_f32 v[150:151], v[128:129], v[222:223], v[150:151]
	v_add_f32_e32 v98, 1.0, v98
	v_rcp_f32_e32 v219, v98
	v_mul_f32_e32 v98, v150, v150
	v_fmamk_f32 v98, v98, 0xbdd2d3e8, v196
	v_mul_f32_e32 v98, v150, v98
	v_exp_f32_e32 v98, v98
	v_pk_mul_f32 v[90:91], v[90:91], v[182:183] op_sel_hi:[1,0]
	s_nop 0
	s_nop 0
	v_add_f32_e32 v98, 1.0, v98
	v_rcp_f32_e32 v220, v98
	v_mul_f32_e32 v98, v151, v151
	v_fmamk_f32 v98, v98, 0xbdd2d3e8, v196
	v_mul_f32_e32 v98, v151, v98
	v_exp_f32_e32 v98, v98
	v_mov_b32_dpp v103, v90 row_ror:1 row_mask:0xf bank_mask:0xf
	v_mov_b32_dpp v141, v91 row_ror:1 row_mask:0xf bank_mask:0xf
	s_nop 0
	v_add_f32_e32 v98, 1.0, v98
	s_nop 0
	s_nop 0
	s_nop 0
	v_rcp_f32_e32 v221, v98
	v_mov_b32_dpp v105, v200 row_ror:1 row_mask:0xf bank_mask:0xf
	v_mov_b32_dpp v142, v201 row_ror:1 row_mask:0xf bank_mask:0xf
	v_mov_b32_dpp v140, v90 row_ror:2 row_mask:0xf bank_mask:0xf
	v_mov_b32_dpp v143, v91 row_ror:2 row_mask:0xf bank_mask:0xf
	s_nop 0
	s_nop 0
	v_cndmask_b32_e64 v229, v141, 0, s[6:7]
	v_cndmask_b32_e64 v228, v103, 0, s[6:7]
	v_pk_fma_f32 v[90:91], v[90:91], v[106:107], v[118:119]
	v_mov_b32_dpp v144, v200 row_ror:2 row_mask:0xf bank_mask:0xf
	v_mov_b32_dpp v145, v201 row_ror:2 row_mask:0xf bank_mask:0xf
	v_cndmask_b32_e64 v227, v142, 0, s[6:7]
	v_cndmask_b32_e64 v226, v105, 0, s[6:7]
	v_cndmask_b32_e64 v233, 0, v143, s[10:11]
	v_cndmask_b32_e64 v232, 0, v140, s[10:11]
	v_pk_fma_f32 v[200:201], v[200:201], v[108:109], v[120:121]
	v_pk_fma_f32 v[90:91], v[114:115], v[228:229], v[90:91]
	v_cndmask_b32_e64 v231, 0, v145, s[10:11]
	v_cndmask_b32_e64 v230, 0, v144, s[10:11]
	v_pk_fma_f32 v[200:201], v[116:117], v[226:227], v[200:201]
	v_pk_fma_f32 v[90:91], v[134:135], v[232:233], v[90:91]
	v_pk_mul_f32 v[152:153], v[152:153], v[218:219]
	v_add_u32_e32 v179, 0x80, v186
	v_pk_fma_f32 v[200:201], v[136:137], v[230:231], v[200:201]
	v_pk_mul_f32 v[150:151], v[150:151], v[220:221]
	v_pk_mul_f32 v[90:91], v[90:91], v[152:153]
	v_pk_mul_f32 v[150:151], v[200:201], v[150:151]
	v_cvt_pk_bf16_f32 v90, v90, v91
	s_nop 0
	v_cvt_pk_bf16_f32 v91, v150, v151
	s_and_saveexec_b64 s[48:49], s[10:11]
	s_cbranch_execz .LBB0_58
	v_mov_b64_e32 v[150:151], s[68:69]
	v_mad_i64_i32 v[150:151], s[50:51], v179, s41, v[150:151]
	v_lshl_add_u64 v[150:151], v[180:181], 1, v[150:151]
	global_store_dwordx2 v[150:151], v[90:91], off
; __device__ __forceinline__ unsigned cvt_pk_bf16(float lo, float hi) { unsigned r; asm volatile("v_cvt_pk_bf16_f32 %0, %1, %2" : "=v"(r) : "v"(lo), "v"(hi)); return r; }
; __device__ __forceinline__ f32x4 gelu4(f32x4 v) { return (f32x4){gelu_t(v[0]), gelu_t(v[1]), gelu_t(v[2]), gelu_t(v[3])}; }
; template <int CTRL> __device__ __forceinline__ f32x4 dpp4(f32x4 v) { return (f32x4){dpp_f<CTRL>(v[0]), dpp_f<CTRL>(v[1]), dpp_f<CTRL>(v[2]), dpp_f<CTRL>(v[3])}; }
;     __device__ __forceinline__ void operator()(const f32x4 (&acc)[2][2][4][2], const Unit& u, int wr, int wc, int fr, int fq) const {
;     ...
;                 for (int m = 0; m < 4; ++m) rs[ai][m] = rsqrtf(ss[row0 + ai * HALF + m * 16] * (1.f / 2048.f) + 1e-6f);
;     ...
;                     for (int m = 0; m < 4; ++m) {
;                         const f32x4 g = acc[ai][0][m][n] * rs[ai][m], v = acc[ai][1][m][n] * rs[ai][m];
;                         const f32x4 g1 = dpp4<0x121>(g), g2 = dpp4<0x122>(g), v1 = dpp4<0x121>(v), v2 = dpp4<0x122>(v);
;                         const f32x4 gp1 = (fr >= 1) ? g1 : pg1, gp2 = (fr >= 2) ? g2 : pg2, vp1 = (fr >= 1) ? v1 : pv1, vp2 = (fr >= 2) ? v2 : pv2;
;                         const f32x4 cgt = bg + wg0 * g + wg1 * gp1 + wg2 * gp2, cvl = bv + wv0 * v + wv1 * vp1 + wv2 * vp2;
;                         const f32x4 o = gelu4(cgt) * cvl;
;                         typedef unsigned u32x2e __attribute__((ext_vector_type(2)));
;                         u32x2e w; w.x = cvt_pk_bf16(o[0], o[1]); w.y = cvt_pk_bf16(o[2], o[3]);
;                         if (!(m == 0 && fr < 2)) *(u32x2e*)((bf16_t*)O + (size_t)(row0 + ai * HALF + m * 16) * DFFc + c) = w;
;                         pg1 = g1; pg2 = g2; pv1 = v1; pv2 = v2;
.LBB0_58:
	s_or_b64 exec, exec, s[48:49]
	v_fmamk_f32 v90, v185, 0x3a000000, v197
	v_cmp_gt_f32_e32 vcc, s67, v90
	v_mul_f32_e32 v98, 0x4b800000, v90
	s_nop 0
	v_cndmask_b32_e32 v90, v90, v98, vcc
	v_rsq_f32_e32 v90, v90
	s_nop 0
	s_nop 0
	s_nop 0
	v_mul_f32_e32 v98, 0x45800000, v90
	v_cndmask_b32_e32 v102, v90, v98, vcc
	v_fmamk_f32 v90, v183, 0x3a000000, v197
	v_pk_mul_f32 v[86:87], v[86:87], v[102:103] op_sel_hi:[1,0]
	s_nop 0
	v_pk_mul_f32 v[88:89], v[88:89], v[102:103] op_sel_hi:[1,0]
	v_mov_b32_dpp v157, v86 row_ror:1 row_mask:0xf bank_mask:0xf
	v_mov_b32_dpp v183, v87 row_ror:1 row_mask:0xf bank_mask:0xf
	s_nop 0
	v_mov_b32_dpp v185, v88 row_ror:1 row_mask:0xf bank_mask:0xf
	v_mov_b32_dpp v187, v89 row_ror:1 row_mask:0xf bank_mask:0xf
	v_mov_b32_dpp v199, v86 row_ror:2 row_mask:0xf bank_mask:0xf
	v_mov_b32_dpp v205, v87 row_ror:2 row_mask:0xf bank_mask:0xf
	s_nop 0
	s_nop 0
	v_cndmask_b32_e64 v93, v183, v93, s[6:7]
	v_cndmask_b32_e64 v92, v157, v92, s[6:7]
	v_pk_fma_f32 v[86:87], v[86:87], v[110:111], v[122:123]
	v_mov_b32_dpp v206, v88 row_ror:2 row_mask:0xf bank_mask:0xf
	v_mov_b32_dpp v207, v89 row_ror:2 row_mask:0xf bank_mask:0xf
	v_cndmask_b32_e64 v151, v187, v97, s[6:7]
	v_cndmask_b32_e64 v150, v185, v94, s[6:7]
	v_cndmask_b32_e64 v153, v99, v205, s[10:11]
	v_cndmask_b32_e64 v152, v95, v199, s[10:11]
	v_pk_fma_f32 v[88:89], v[88:89], v[112:113], v[124:125]
	v_pk_fma_f32 v[86:87], v[130:131], v[92:93], v[86:87]
	v_cndmask_b32_e64 v95, v104, v207, s[10:11]
	v_cndmask_b32_e64 v94, v96, v206, s[10:11]
	v_pk_fma_f32 v[88:89], v[132:133], v[150:151], v[88:89]
	v_pk_fma_f32 v[86:87], v[126:127], v[152:153], v[86:87]
	v_pk_fma_f32 v[88:89], v[128:129], v[94:95], v[88:89]
	v_mul_f32_e32 v92, v86, v86
	v_mul_f32_e32 v93, v87, v87
	v_fmamk_f32 v92, v92, 0xbdd2d3e8, v196
	v_fmamk_f32 v93, v93, 0xbdd2d3e8, v196
	v_mul_f32_e32 v94, v88, v88
	v_mul_f32_e32 v95, v89, v89
	v_mul_f32_e32 v92, v86, v92
	v_mul_f32_e32 v93, v87, v93
	v_fmamk_f32 v94, v94, 0xbdd2d3e8, v196
	v_fmamk_f32 v95, v95, 0xbdd2d3e8, v196
	v_exp_f32_e32 v92, v92
	v_exp_f32_e32 v93, v93
	v_mul_f32_e32 v94, v88, v94
	v_mul_f32_e32 v95, v89, v95
	v_exp_f32_e32 v94, v94
	v_exp_f32_e32 v95, v95
	v_cmp_gt_f32_e32 vcc, s67, v90
	v_mul_f32_e32 v98, 0x4b800000, v90
	v_add_f32_e32 v92, 1.0, v92
	v_add_f32_e32 v93, 1.0, v93
	v_cndmask_b32_e32 v90, v90, v98, vcc
	v_pk_mul_f32 v[82:83], v[82:83], v[102:103] op_sel_hi:[1,0]
	s_nop 0
	s_nop 0
	v_rcp_f32_e32 v92, v92
	v_rcp_f32_e32 v93, v93
	v_add_f32_e32 v94, 1.0, v94
	v_add_f32_e32 v95, 1.0, v95
	v_rsq_f32_e32 v90, v90
	v_pk_mul_f32 v[84:85], v[84:85], v[102:103] op_sel_hi:[1,0]
	v_mov_b32_dpp v208, v82 row_ror:1 row_mask:0xf bank_mask:0xf
	v_mov_b32_dpp v209, v83 row_ror:1 row_mask:0xf bank_mask:0xf
	s_nop 0
	s_nop 0
	s_nop 0
	s_nop 0
	v_rcp_f32_e32 v94, v94
	v_rcp_f32_e32 v95, v95
	v_mov_b32_dpp v210, v84 row_ror:1 row_mask:0xf bank_mask:0xf
	v_mov_b32_dpp v211, v85 row_ror:1 row_mask:0xf bank_mask:0xf
	v_mov_b32_dpp v218, v82 row_ror:2 row_mask:0xf bank_mask:0xf
	v_mov_b32_dpp v219, v83 row_ror:2 row_mask:0xf bank_mask:0xf
	s_nop 0
	s_nop 0
	v_cndmask_b32_e64 v97, v209, v141, s[6:7]
	v_cndmask_b32_e64 v96, v208, v103, s[6:7]
	v_pk_fma_f32 v[82:83], v[82:83], v[106:107], v[118:119]
	v_mov_b32_dpp v220, v84 row_ror:2 row_mask:0xf bank_mask:0xf
	v_mov_b32_dpp v221, v85 row_ror:2 row_mask:0xf bank_mask:0xf
	v_cndmask_b32_e64 v201, v211, v142, s[6:7]
	v_cndmask_b32_e64 v200, v210, v105, s[6:7]
	v_cndmask_b32_e64 v141, v143, v219, s[10:11]
	v_cndmask_b32_e64 v140, v140, v218, s[10:11]
	v_pk_fma_f32 v[84:85], v[84:85], v[108:109], v[120:121]
	v_pk_fma_f32 v[82:83], v[114:115], v[96:97], v[82:83]
	v_cndmask_b32_e64 v105, v145, v221, s[10:11]
	v_cndmask_b32_e64 v104, v144, v220, s[10:11]
	v_pk_fma_f32 v[84:85], v[116:117], v[200:201], v[84:85]
	v_pk_fma_f32 v[82:83], v[134:135], v[140:141], v[82:83]
	v_pk_mul_f32 v[86:87], v[86:87], v[92:93]
	v_mul_f32_e32 v98, 0x45800000, v90
	v_pk_fma_f32 v[84:85], v[136:137], v[104:105], v[84:85]
	v_pk_mul_f32 v[88:89], v[88:89], v[94:95]
	v_pk_mul_f32 v[82:83], v[82:83], v[86:87]
	v_add_u32_e32 v91, 0x90, v186
	v_cndmask_b32_e32 v98, v90, v98, vcc
	v_pk_mul_f32 v[84:85], v[84:85], v[88:89]
	v_cvt_pk_bf16_f32 v86, v82, v83
	v_mov_b64_e32 v[82:83], s[68:69]
	v_cvt_pk_bf16_f32 v87, v84, v85
	v_mad_i64_i32 v[84:85], s[48:49], v91, s41, v[82:83]
	v_pk_mul_f32 v[80:81], v[80:81], v[98:99] op_sel_hi:[1,0]
	v_pk_mul_f32 v[78:79], v[78:79], v[98:99] op_sel_hi:[1,0]
	v_pk_mul_f32 v[76:77], v[76:77], v[98:99] op_sel_hi:[1,0]
	v_pk_mul_f32 v[74:75], v[74:75], v[98:99] op_sel_hi:[1,0]
	s_nop 0
	s_nop 0
	s_nop 0
	s_nop 0
	v_lshl_add_u64 v[104:105], v[84:85], 0, v[148:149]
	v_mov_b32_dpp v91, v78 row_ror:1 row_mask:0xf bank_mask:0xf
	v_mov_b32_dpp v99, v79 row_ror:1 row_mask:0xf bank_mask:0xf
	v_mov_b32_dpp v103, v80 row_ror:1 row_mask:0xf bank_mask:0xf
	v_mov_b32_dpp v144, v81 row_ror:1 row_mask:0xf bank_mask:0xf
	s_nop 0
	s_nop 0
	s_nop 0
	s_nop 0
	global_store_dwordx2 v[104:105], v[86:87], off
	v_mov_b32_dpp v145, v78 row_ror:2 row_mask:0xf bank_mask:0xf
	v_mov_b32_dpp v150, v79 row_ror:2 row_mask:0xf bank_mask:0xf
	v_mov_b32_dpp v151, v80 row_ror:2 row_mask:0xf bank_mask:0xf
	v_mov_b32_dpp v152, v81 row_ror:2 row_mask:0xf bank_mask:0xf
	v_cndmask_b32_e64 v85, v144, v187, s[6:7]
	v_cndmask_b32_e64 v84, v103, v185, s[6:7]
	v_cndmask_b32_e64 v87, v99, v183, s[6:7]
	v_cndmask_b32_e64 v86, v91, v157, s[6:7]
	v_pk_fma_f32 v[80:81], v[80:81], v[112:113], v[124:125]
	v_pk_fma_f32 v[78:79], v[78:79], v[110:111], v[122:123]
	v_cndmask_b32_e64 v89, v205, v150, s[10:11]
	v_cndmask_b32_e64 v88, v199, v145, s[10:11]
; __device__ __forceinline__ unsigned cvt_pk_bf16(float lo, float hi) { unsigned r; asm volatile("v_cvt_pk_bf16_f32 %0, %1, %2" : "=v"(r) : "v"(lo), "v"(hi)); return r; }
; __device__ __forceinline__ f32x4 gelu4(f32x4 v) { return (f32x4){gelu_t(v[0]), gelu_t(v[1]), gelu_t(v[2]), gelu_t(v[3])}; }
; template <int CTRL> __device__ __forceinline__ f32x4 dpp4(f32x4 v) { return (f32x4){dpp_f<CTRL>(v[0]), dpp_f<CTRL>(v[1]), dpp_f<CTRL>(v[2]), dpp_f<CTRL>(v[3])}; }
;     __device__ __forceinline__ void operator()(const f32x4 (&acc)[2][2][4][2], const Unit& u, int wr, int wc, int fr, int fq) const {
;     ...
;                     for (int m = 0; m < 4; ++m) {
;                         const f32x4 g = acc[ai][0][m][n] * rs[ai][m], v = acc[ai][1][m][n] * rs[ai][m];
;                         const f32x4 g1 = dpp4<0x121>(g), g2 = dpp4<0x122>(g), v1 = dpp4<0x121>(v), v2 = dpp4<0x122>(v);
;                         const f32x4 gp1 = (fr >= 1) ? g1 : pg1, gp2 = (fr >= 2) ? g2 : pg2, vp1 = (fr >= 1) ? v1 : pv1, vp2 = (fr >= 2) ? v2 : pv2;
;                         const f32x4 cgt = bg + wg0 * g + wg1 * gp1 + wg2 * gp2, cvl = bv + wv0 * v + wv1 * vp1 + wv2 * vp2;
;                         const f32x4 o = gelu4(cgt) * cvl;
;                         typedef unsigned u32x2e __attribute__((ext_vector_type(2)));
;                         u32x2e w; w.x = cvt_pk_bf16(o[0], o[1]); w.y = cvt_pk_bf16(o[2], o[3]);
;                         if (!(m == 0 && fr < 2)) *(u32x2e*)((bf16_t*)O + (size_t)(row0 + ai * HALF + m * 16) * DFFc + c) = w;
;                         pg1 = g1; pg2 = g2; pv1 = v1; pv2 = v2;
	v_cndmask_b32_e64 v93, v207, v152, s[10:11]
	v_cndmask_b32_e64 v92, v206, v151, s[10:11]
	v_pk_fma_f32 v[78:79], v[130:131], v[86:87], v[78:79]
	v_pk_fma_f32 v[80:81], v[132:133], v[84:85], v[80:81]
	v_pk_fma_f32 v[78:79], v[126:127], v[88:89], v[78:79]
	v_pk_fma_f32 v[80:81], v[128:129], v[92:93], v[80:81]
	v_mul_f32_e32 v84, v78, v78
	v_mul_f32_e32 v85, v79, v79
	v_mul_f32_e32 v86, v80, v80
	v_mul_f32_e32 v87, v81, v81
	v_fmamk_f32 v84, v84, 0xbdd2d3e8, v196
	v_fmamk_f32 v85, v85, 0xbdd2d3e8, v196
	v_fmamk_f32 v86, v86, 0xbdd2d3e8, v196
	v_fmamk_f32 v87, v87, 0xbdd2d3e8, v196
	v_mul_f32_e32 v84, v78, v84
	v_mul_f32_e32 v85, v79, v85
	v_mul_f32_e32 v86, v80, v86
	v_mul_f32_e32 v87, v81, v87
	v_exp_f32_e32 v84, v84
	v_exp_f32_e32 v85, v85
	v_exp_f32_e32 v86, v86
	v_exp_f32_e32 v87, v87
	v_add_f32_e32 v84, 1.0, v84
	v_add_f32_e32 v85, 1.0, v85
	v_add_f32_e32 v86, 1.0, v86
	v_add_f32_e32 v87, 1.0, v87
	s_nop 0
	s_nop 0
	s_nop 0
	s_nop 0
	v_rcp_f32_e32 v84, v84
	v_rcp_f32_e32 v85, v85
	v_rcp_f32_e32 v86, v86
	v_rcp_f32_e32 v87, v87
	v_mov_b32_dpp v153, v74 row_ror:1 row_mask:0xf bank_mask:0xf
	v_mov_b32_dpp v200, v75 row_ror:1 row_mask:0xf bank_mask:0xf
	v_mov_b32_dpp v201, v76 row_ror:1 row_mask:0xf bank_mask:0xf
	v_mov_b32_dpp v222, v77 row_ror:1 row_mask:0xf bank_mask:0xf
	s_nop 0
	s_nop 0
	s_nop 0
	s_nop 0
	v_mov_b32_dpp v223, v74 row_ror:2 row_mask:0xf bank_mask:0xf
	v_mov_b32_dpp v224, v75 row_ror:2 row_mask:0xf bank_mask:0xf
	v_mov_b32_dpp v225, v76 row_ror:2 row_mask:0xf bank_mask:0xf
	v_mov_b32_dpp v226, v77 row_ror:2 row_mask:0xf bank_mask:0xf
	v_cndmask_b32_e64 v95, v200, v209, s[6:7]
	v_cndmask_b32_e64 v94, v153, v208, s[6:7]
	v_cndmask_b32_e64 v97, v222, v211, s[6:7]
	v_cndmask_b32_e64 v96, v201, v210, s[6:7]
	v_pk_fma_f32 v[74:75], v[74:75], v[106:107], v[118:119]
	v_pk_fma_f32 v[76:77], v[76:77], v[108:109], v[120:121]
	v_cndmask_b32_e64 v141, v221, v226, s[10:11]
	v_cndmask_b32_e64 v140, v220, v225, s[10:11]
	v_cndmask_b32_e64 v143, v219, v224, s[10:11]
	v_cndmask_b32_e64 v142, v218, v223, s[10:11]
	v_pk_fma_f32 v[76:77], v[116:117], v[96:97], v[76:77]
	v_pk_fma_f32 v[74:75], v[114:115], v[94:95], v[74:75]
	v_pk_fma_f32 v[76:77], v[136:137], v[140:141], v[76:77]
	v_pk_fma_f32 v[74:75], v[134:135], v[142:143], v[74:75]
	v_pk_mul_f32 v[78:79], v[78:79], v[84:85]
	v_pk_mul_f32 v[80:81], v[80:81], v[86:87]
	v_add_u32_e32 v155, 0xa0, v186
	v_pk_mul_f32 v[76:77], v[76:77], v[80:81]
	v_pk_mul_f32 v[74:75], v[74:75], v[78:79]
	v_pk_mul_f32 v[72:73], v[72:73], v[178:179] op_sel_hi:[1,0]
	v_cvt_pk_bf16_f32 v74, v74, v75
	v_cvt_pk_bf16_f32 v75, v76, v77
	v_mad_i64_i32 v[76:77], s[48:49], v155, s41, v[82:83]
	v_lshl_add_u64 v[140:141], v[76:77], 0, v[148:149]
	global_store_dwordx2 v[140:141], v[74:75], off
	v_pk_mul_f32 v[70:71], v[70:71], v[178:179] op_sel_hi:[1,0]
	s_nop 0
	s_nop 0
	s_nop 0
	s_nop 0
	v_mov_b32_dpp v76, v70 row_ror:1 row_mask:0xf bank_mask:0xf
	v_mov_b32_dpp v77, v71 row_ror:1 row_mask:0xf bank_mask:0xf
	v_mov_b32_dpp v74, v72 row_ror:1 row_mask:0xf bank_mask:0xf
	v_mov_b32_dpp v75, v73 row_ror:1 row_mask:0xf bank_mask:0xf
	s_nop 0
	s_nop 0
	s_nop 0
	s_nop 0
	v_mov_b32_dpp v78, v70 row_ror:2 row_mask:0xf bank_mask:0xf
	v_mov_b32_dpp v79, v71 row_ror:2 row_mask:0xf bank_mask:0xf
	v_mov_b32_dpp v80, v72 row_ror:2 row_mask:0xf bank_mask:0xf
	v_mov_b32_dpp v81, v73 row_ror:2 row_mask:0xf bank_mask:0xf
	v_cndmask_b32_e64 v75, v75, v144, s[6:7]
	v_cndmask_b32_e64 v74, v74, v103, s[6:7]
	v_cndmask_b32_e64 v77, v77, v99, s[6:7]
	v_cndmask_b32_e64 v76, v76, v91, s[6:7]
	v_pk_fma_f32 v[72:73], v[72:73], v[112:113], v[124:125]
	v_pk_fma_f32 v[70:71], v[70:71], v[110:111], v[122:123]
	v_cndmask_b32_e64 v79, v150, v79, s[10:11]
	v_cndmask_b32_e64 v78, v145, v78, s[10:11]
	v_cndmask_b32_e64 v81, v152, v81, s[10:11]
	v_cndmask_b32_e64 v80, v151, v80, s[10:11]
	v_pk_fma_f32 v[70:71], v[130:131], v[76:77], v[70:71]
	v_pk_fma_f32 v[72:73], v[132:133], v[74:75], v[72:73]
	v_pk_fma_f32 v[70:71], v[126:127], v[78:79], v[70:71]
	v_pk_fma_f32 v[72:73], v[128:129], v[80:81], v[72:73]
	v_mul_f32_e32 v74, v70, v70
	v_mul_f32_e32 v75, v71, v71
	v_mul_f32_e32 v76, v72, v72
	v_mul_f32_e32 v77, v73, v73
	v_fmamk_f32 v74, v74, 0xbdd2d3e8, v196
	v_fmamk_f32 v75, v75, 0xbdd2d3e8, v196
	v_fmamk_f32 v76, v76, 0xbdd2d3e8, v196
	v_fmamk_f32 v77, v77, 0xbdd2d3e8, v196
	v_mul_f32_e32 v74, v70, v74
	v_mul_f32_e32 v75, v71, v75
	v_mul_f32_e32 v76, v72, v76
	v_mul_f32_e32 v77, v73, v77
	v_exp_f32_e32 v74, v74
	v_exp_f32_e32 v75, v75
	v_exp_f32_e32 v76, v76
	v_exp_f32_e32 v77, v77
	v_add_f32_e32 v74, 1.0, v74
	v_add_f32_e32 v75, 1.0, v75
	v_add_f32_e32 v76, 1.0, v76
	v_add_f32_e32 v77, 1.0, v77
	v_pk_mul_f32 v[68:69], v[68:69], v[178:179] op_sel_hi:[1,0]
	v_pk_mul_f32 v[66:67], v[66:67], v[178:179] op_sel_hi:[1,0]
	s_nop 0
	s_nop 0
	s_nop 0
	s_nop 0
	v_rcp_f32_e32 v74, v74
	v_rcp_f32_e32 v75, v75
	v_rcp_f32_e32 v76, v76
	v_rcp_f32_e32 v77, v77
	v_mov_b32_dpp v84, v66 row_ror:1 row_mask:0xf bank_mask:0xf
	v_mov_b32_dpp v85, v67 row_ror:1 row_mask:0xf bank_mask:0xf
	v_mov_b32_dpp v86, v68 row_ror:1 row_mask:0xf bank_mask:0xf
	v_mov_b32_dpp v87, v69 row_ror:1 row_mask:0xf bank_mask:0xf
	s_nop 0
	s_nop 0
	s_nop 0
	s_nop 0
	v_mov_b32_dpp v92, v66 row_ror:2 row_mask:0xf bank_mask:0xf
	v_mov_b32_dpp v93, v67 row_ror:2 row_mask:0xf bank_mask:0xf
	v_mov_b32_dpp v88, v68 row_ror:2 row_mask:0xf bank_mask:0xf
	v_mov_b32_dpp v89, v69 row_ror:2 row_mask:0xf bank_mask:0xf
	v_cndmask_b32_e64 v85, v85, v200, s[6:7]
	v_cndmask_b32_e64 v84, v84, v153, s[6:7]
	v_cndmask_b32_e64 v87, v87, v222, s[6:7]
	v_cndmask_b32_e64 v86, v86, v201, s[6:7]
	v_pk_fma_f32 v[68:69], v[68:69], v[108:109], v[120:121]
; __device__ __forceinline__ unsigned cvt_pk_bf16(float lo, float hi) { unsigned r; asm volatile("v_cvt_pk_bf16_f32 %0, %1, %2" : "=v"(r) : "v"(lo), "v"(hi)); return r; }
; __device__ __forceinline__ f32x4 gelu4(f32x4 v) { return (f32x4){gelu_t(v[0]), gelu_t(v[1]), gelu_t(v[2]), gelu_t(v[3])}; }
; template <int CTRL> __device__ __forceinline__ f32x4 dpp4(f32x4 v) { return (f32x4){dpp_f<CTRL>(v[0]), dpp_f<CTRL>(v[1]), dpp_f<CTRL>(v[2]), dpp_f<CTRL>(v[3])}; }
;     __device__ __forceinline__ void operator()(const f32x4 (&acc)[2][2][4][2], const Unit& u, int wr, int wc, int fr, int fq) const {
;     ...
;             for (int n = 0; n < 2; ++n) {
;                 const int c = cgl + 4 * n;
;                 const f32x4 wg0 = *(const f32x4*)(bias + c), wg1 = *(const f32x4*)(bias + NUPc + c), wg2 = *(const f32x4*)(bias + 2 * NUPc + c), bg = *(const f32x4*)(xin + c);
;                 const f32x4 wv0 = *(const f32x4*)(bias + DFFc + c), wv1 = *(const f32x4*)(bias + NUPc + DFFc + c), wv2 = *(const f32x4*)(bias + 2 * NUPc + DFFc + c), bv = *(const f32x4*)(xin + DFFc + c);
; #pragma unroll
;                 for (int ai = 0; ai < 2; ++ai) {
;                     f32x4 pg1 = (f32x4){0.f, 0.f, 0.f, 0.f}, pg2 = pg1, pv1 = pg1, pv2 = pg1;
; #pragma unroll
;                     for (int m = 0; m < 4; ++m) {
;                         const f32x4 g = acc[ai][0][m][n] * rs[ai][m], v = acc[ai][1][m][n] * rs[ai][m];
;                         const f32x4 g1 = dpp4<0x121>(g), g2 = dpp4<0x122>(g), v1 = dpp4<0x121>(v), v2 = dpp4<0x122>(v);
;                         const f32x4 gp1 = (fr >= 1) ? g1 : pg1, gp2 = (fr >= 2) ? g2 : pg2, vp1 = (fr >= 1) ? v1 : pv1, vp2 = (fr >= 2) ? v2 : pv2;
;                         const f32x4 cgt = bg + wg0 * g + wg1 * gp1 + wg2 * gp2, cvl = bv + wv0 * v + wv1 * vp1 + wv2 * vp2;
;                         const f32x4 o = gelu4(cgt) * cvl;
;                         typedef unsigned u32x2e __attribute__((ext_vector_type(2)));
;                         u32x2e w; w.x = cvt_pk_bf16(o[0], o[1]); w.y = cvt_pk_bf16(o[2], o[3]);
;                         if (!(m == 0 && fr < 2)) *(u32x2e*)((bf16_t*)O + (size_t)(row0 + ai * HALF + m * 16) * DFFc + c) = w;
;                         pg1 = g1; pg2 = g2; pv1 = v1; pv2 = v2;
	v_pk_fma_f32 v[66:67], v[66:67], v[106:107], v[118:119]
	v_cndmask_b32_e64 v89, v226, v89, s[10:11]
	v_cndmask_b32_e64 v88, v225, v88, s[10:11]
	v_cndmask_b32_e64 v93, v224, v93, s[10:11]
	v_cndmask_b32_e64 v92, v223, v92, s[10:11]
	v_pk_fma_f32 v[68:69], v[116:117], v[86:87], v[68:69]
	v_pk_fma_f32 v[66:67], v[114:115], v[84:85], v[66:67]
	v_pk_fma_f32 v[68:69], v[136:137], v[88:89], v[68:69]
	v_pk_fma_f32 v[66:67], v[134:135], v[92:93], v[66:67]
	v_pk_mul_f32 v[70:71], v[70:71], v[74:75]
	v_pk_mul_f32 v[72:73], v[72:73], v[76:77]
	v_add_u32_e32 v90, 0xb0, v186
	v_pk_mul_f32 v[68:69], v[68:69], v[72:73]
	v_pk_mul_f32 v[66:67], v[66:67], v[70:71]
	v_mov_b32_e32 v189, v188
	v_cvt_pk_bf16_f32 v66, v66, v67
	v_cvt_pk_bf16_f32 v67, v68, v69
	v_mad_i64_i32 v[68:69], s[48:49], v90, s41, v[82:83]
	v_lshl_add_u64 v[106:107], v[68:69], 0, v[148:149]
	global_store_dwordx2 v[106:107], v[66:67], off
	v_or_b32_e32 v66, 4, v180
	v_ashrrev_i32_e32 v67, 31, v66
	v_lshlrev_b64 v[94:95], 2, v[66:67]
	v_lshl_add_u64 v[66:67], s[26:27], 0, v[94:95]
	global_load_dwordx4 v[86:89], v[192:193], off offset:16
	global_load_dwordx4 v[82:85], v[66:67], off
	v_lshl_add_u64 v[66:67], s[28:29], 0, v[94:95]
	global_load_dwordx4 v[78:81], v[66:67], off
	global_load_dwordx4 v[90:93], v[190:191], off offset:16
	v_lshl_add_u64 v[66:67], s[30:31], 0, v[94:95]
	global_load_dwordx4 v[70:73], v[66:67], off
	v_lshl_add_u64 v[66:67], s[34:35], 0, v[94:95]
	global_load_dwordx4 v[74:77], v[66:67], off
	v_lshl_add_u64 v[66:67], s[36:37], 0, v[94:95]
	v_lshl_add_u64 v[94:95], s[38:39], 0, v[94:95]
	global_load_dwordx4 v[94:97], v[94:95], off
	v_mov_b32_e32 v108, v188
	global_load_dwordx4 v[66:69], v[66:67], off
	v_mov_b32_e32 v109, v188
	v_pk_mul_f32 v[118:119], v[62:63], v[188:189]
	v_pk_mul_f32 v[120:121], v[60:61], v[108:109]
	s_nop 0
	s_nop 0
	v_pk_mul_f32 v[116:117], v[64:65], v[108:109]
	v_mov_b32_dpp v60, v118 row_ror:1 row_mask:0xf bank_mask:0xf
	v_mov_b32_dpp v61, v119 row_ror:1 row_mask:0xf bank_mask:0xf
	s_nop 0
	s_nop 0
	s_nop 0
	s_nop 0
	v_mov_b32_dpp v63, v116 row_ror:1 row_mask:0xf bank_mask:0xf
	v_mov_b32_dpp v99, v117 row_ror:1 row_mask:0xf bank_mask:0xf
	v_mov_b32_dpp v62, v118 row_ror:2 row_mask:0xf bank_mask:0xf
	v_mov_b32_dpp v64, v119 row_ror:2 row_mask:0xf bank_mask:0xf
	s_nop 0
	s_nop 0
	v_cndmask_b32_e64 v125, v61, 0, s[6:7]
	v_cndmask_b32_e64 v124, v60, 0, s[6:7]
	v_mov_b32_dpp v103, v116 row_ror:2 row_mask:0xf bank_mask:0xf
	v_mov_b32_dpp v110, v117 row_ror:2 row_mask:0xf bank_mask:0xf
	v_cndmask_b32_e64 v123, v99, 0, s[6:7]
	v_cndmask_b32_e64 v122, v63, 0, s[6:7]
	v_cndmask_b32_e64 v129, 0, v64, s[10:11]
	v_cndmask_b32_e64 v128, 0, v62, s[10:11]
	v_cndmask_b32_e64 v127, 0, v110, s[10:11]
	v_cndmask_b32_e64 v126, 0, v103, s[10:11]
	v_pk_mul_f32 v[58:59], v[58:59], v[188:189]
	s_nop 0
	s_nop 0
	s_nop 0
	v_mov_b32_dpp v65, v58 row_ror:1 row_mask:0xf bank_mask:0xf
	v_mov_b32_dpp v108, v59 row_ror:1 row_mask:0xf bank_mask:0xf
	s_nop 0
	s_nop 0
	s_nop 0
	v_mov_b32_dpp v111, v120 row_ror:1 row_mask:0xf bank_mask:0xf
	v_mov_b32_dpp v113, v121 row_ror:1 row_mask:0xf bank_mask:0xf
	v_mov_b32_dpp v109, v58 row_ror:2 row_mask:0xf bank_mask:0xf
	v_mov_b32_dpp v112, v59 row_ror:2 row_mask:0xf bank_mask:0xf
	s_nop 0
	s_nop 0
	v_cndmask_b32_e64 v133, v108, 0, s[6:7]
	v_cndmask_b32_e64 v132, v65, 0, s[6:7]
	v_mov_b32_dpp v114, v120 row_ror:2 row_mask:0xf bank_mask:0xf
	v_mov_b32_dpp v115, v121 row_ror:2 row_mask:0xf bank_mask:0xf
	v_cndmask_b32_e64 v131, v113, 0, s[6:7]
	v_cndmask_b32_e64 v130, v111, 0, s[6:7]
	v_cndmask_b32_e64 v137, 0, v112, s[10:11]
	v_cndmask_b32_e64 v136, 0, v109, s[10:11]
	v_cndmask_b32_e64 v135, 0, v115, s[10:11]
	v_cndmask_b32_e64 v134, 0, v114, s[10:11]
	s_movk_i32 s76, 0x2c00
	s_waitcnt vmcnt(4)
	v_pk_fma_f32 v[118:119], v[118:119], v[86:87], v[90:91]
	v_pk_fma_f32 v[116:117], v[116:117], v[88:89], v[92:93]
	v_pk_fma_f32 v[118:119], v[82:83], v[124:125], v[118:119]
	v_pk_fma_f32 v[116:117], v[84:85], v[122:123], v[116:117]
	v_pk_fma_f32 v[118:119], v[78:79], v[128:129], v[118:119]
	v_pk_fma_f32 v[116:117], v[80:81], v[126:127], v[116:117]
	v_mul_f32_e32 v122, v118, v118
	v_mul_f32_e32 v123, v119, v119
	v_fmamk_f32 v122, v122, 0xbdd2d3e8, v196
	v_fmamk_f32 v123, v123, 0xbdd2d3e8, v196
	v_mul_f32_e32 v124, v116, v116
	v_mul_f32_e32 v125, v117, v117
	v_mul_f32_e32 v122, v118, v122
	v_mul_f32_e32 v123, v119, v123
	v_fmamk_f32 v124, v124, 0xbdd2d3e8, v196
	v_fmamk_f32 v125, v125, 0xbdd2d3e8, v196
	v_exp_f32_e32 v122, v122
	v_exp_f32_e32 v123, v123
	v_mul_f32_e32 v124, v116, v124
	v_mul_f32_e32 v125, v117, v125
	v_exp_f32_e32 v124, v124
	v_exp_f32_e32 v125, v125
	v_add_f32_e32 v122, 1.0, v122
	v_add_f32_e32 v123, 1.0, v123
	v_rcp_f32_e32 v122, v122
	v_rcp_f32_e32 v123, v123
	v_add_f32_e32 v124, 1.0, v124
	v_add_f32_e32 v125, 1.0, v125
	v_rcp_f32_e32 v124, v124
	v_rcp_f32_e32 v125, v125
	s_waitcnt vmcnt(1)
	v_pk_fma_f32 v[58:59], v[58:59], v[70:71], v[94:95]
	v_pk_fma_f32 v[120:121], v[120:121], v[72:73], v[96:97]
	v_pk_fma_f32 v[58:59], v[74:75], v[132:133], v[58:59]
	v_pk_fma_f32 v[120:121], v[76:77], v[130:131], v[120:121]
	s_waitcnt vmcnt(0)
	v_pk_fma_f32 v[58:59], v[66:67], v[136:137], v[58:59]
	v_pk_mul_f32 v[118:119], v[118:119], v[122:123]
	v_pk_fma_f32 v[120:121], v[68:69], v[134:135], v[120:121]
	v_pk_mul_f32 v[116:117], v[116:117], v[124:125]
	v_pk_mul_f32 v[58:59], v[58:59], v[118:119]
	v_pk_mul_f32 v[116:117], v[120:121], v[116:117]
	v_cvt_pk_bf16_f32 v58, v58, v59
	s_nop 0
	v_cvt_pk_bf16_f32 v59, v116, v117
	s_and_saveexec_b64 s[48:49], s[10:11]
	s_cbranch_execz .LBB0_60
	v_mov_b64_e32 v[116:117], s[68:69]
	v_mad_i64_i32 v[116:117], s[50:51], v186, s76, v[116:117]
	v_lshl_add_u64 v[116:117], v[180:181], 1, v[116:117]
	global_store_dwordx2 v[116:117], v[58:59], off offset:8
; __device__ __forceinline__ unsigned cvt_pk_bf16(float lo, float hi) { unsigned r; asm volatile("v_cvt_pk_bf16_f32 %0, %1, %2" : "=v"(r) : "v"(lo), "v"(hi)); return r; }
; __device__ __forceinline__ f32x4 gelu4(f32x4 v) { return (f32x4){gelu_t(v[0]), gelu_t(v[1]), gelu_t(v[2]), gelu_t(v[3])}; }
; template <int CTRL> __device__ __forceinline__ f32x4 dpp4(f32x4 v) { return (f32x4){dpp_f<CTRL>(v[0]), dpp_f<CTRL>(v[1]), dpp_f<CTRL>(v[2]), dpp_f<CTRL>(v[3])}; }
;     __device__ __forceinline__ void operator()(const f32x4 (&acc)[2][2][4][2], const Unit& u, int wr, int wc, int fr, int fq) const {
;     ...
;                     for (int m = 0; m < 4; ++m) {
;                         const f32x4 g = acc[ai][0][m][n] * rs[ai][m], v = acc[ai][1][m][n] * rs[ai][m];
;                         const f32x4 g1 = dpp4<0x121>(g), g2 = dpp4<0x122>(g), v1 = dpp4<0x121>(v), v2 = dpp4<0x122>(v);
;                         const f32x4 gp1 = (fr >= 1) ? g1 : pg1, gp2 = (fr >= 2) ? g2 : pg2, vp1 = (fr >= 1) ? v1 : pv1, vp2 = (fr >= 2) ? v2 : pv2;
;                         const f32x4 cgt = bg + wg0 * g + wg1 * gp1 + wg2 * gp2, cvl = bv + wv0 * v + wv1 * vp1 + wv2 * vp2;
;                         const f32x4 o = gelu4(cgt) * cvl;
;                         typedef unsigned u32x2e __attribute__((ext_vector_type(2)));
;                         u32x2e w; w.x = cvt_pk_bf16(o[0], o[1]); w.y = cvt_pk_bf16(o[2], o[3]);
;                         if (!(m == 0 && fr < 2)) *(u32x2e*)((bf16_t*)O + (size_t)(row0 + ai * HALF + m * 16) * DFFc + c) = w;
;                         pg1 = g1; pg2 = g2; pv1 = v1; pv2 = v2;
.LBB0_60:
	s_or_b64 exec, exec, s[48:49]
	v_mov_b32_e32 v157, v156
	v_mov_b32_e32 v58, v156
	v_mov_b32_e32 v59, v156
	v_pk_mul_f32 v[54:55], v[54:55], v[156:157]
	s_nop 0
	s_nop 0
	v_pk_mul_f32 v[56:57], v[56:57], v[58:59]
	v_mov_b32_dpp v120, v54 row_ror:1 row_mask:0xf bank_mask:0xf
	v_mov_b32_dpp v121, v55 row_ror:1 row_mask:0xf bank_mask:0xf
	s_nop 0
	s_nop 0
	s_nop 0
	s_nop 0
	v_mov_b32_dpp v122, v56 row_ror:1 row_mask:0xf bank_mask:0xf
	v_mov_b32_dpp v123, v57 row_ror:1 row_mask:0xf bank_mask:0xf
	v_mov_b32_dpp v124, v54 row_ror:2 row_mask:0xf bank_mask:0xf
	v_mov_b32_dpp v125, v55 row_ror:2 row_mask:0xf bank_mask:0xf
	s_nop 0
	s_nop 0
	v_cndmask_b32_e64 v61, v121, v61, s[6:7]
	v_cndmask_b32_e64 v60, v120, v60, s[6:7]
	v_pk_fma_f32 v[54:55], v[54:55], v[86:87], v[90:91]
	v_pk_mul_f32 v[52:53], v[52:53], v[58:59]
	v_mov_b32_dpp v126, v56 row_ror:2 row_mask:0xf bank_mask:0xf
	v_mov_b32_dpp v127, v57 row_ror:2 row_mask:0xf bank_mask:0xf
	v_cndmask_b32_e64 v59, v123, v99, s[6:7]
	v_cndmask_b32_e64 v58, v122, v63, s[6:7]
	v_cndmask_b32_e64 v63, v64, v125, s[10:11]
	v_cndmask_b32_e64 v62, v62, v124, s[10:11]
	v_pk_fma_f32 v[56:57], v[56:57], v[88:89], v[92:93]
	v_pk_fma_f32 v[54:55], v[82:83], v[60:61], v[54:55]
	v_cndmask_b32_e64 v117, v110, v127, s[10:11]
	v_cndmask_b32_e64 v116, v103, v126, s[10:11]
	v_pk_fma_f32 v[56:57], v[84:85], v[58:59], v[56:57]
	v_pk_fma_f32 v[54:55], v[78:79], v[62:63], v[54:55]
	v_pk_fma_f32 v[56:57], v[80:81], v[116:117], v[56:57]
	v_mul_f32_e32 v58, v54, v54
	v_mul_f32_e32 v59, v55, v55
	v_fmamk_f32 v58, v58, 0xbdd2d3e8, v196
	v_fmamk_f32 v59, v59, 0xbdd2d3e8, v196
	v_mul_f32_e32 v60, v56, v56
	v_mul_f32_e32 v61, v57, v57
	v_mul_f32_e32 v58, v54, v58
	v_mul_f32_e32 v59, v55, v59
	v_fmamk_f32 v60, v60, 0xbdd2d3e8, v196
	v_fmamk_f32 v61, v61, 0xbdd2d3e8, v196
	v_exp_f32_e32 v58, v58
	v_exp_f32_e32 v59, v59
	v_mul_f32_e32 v60, v56, v60
	v_mul_f32_e32 v61, v57, v61
	v_exp_f32_e32 v60, v60
	v_exp_f32_e32 v61, v61
	v_add_f32_e32 v58, 1.0, v58
	v_add_f32_e32 v59, 1.0, v59
	v_pk_mul_f32 v[50:51], v[50:51], v[156:157]
	s_nop 0
	s_nop 0
	s_nop 0
	v_rcp_f32_e32 v58, v58
	v_add_f32_e32 v60, 1.0, v60
	v_add_f32_e32 v61, 1.0, v61
	v_rcp_f32_e32 v59, v59
	v_mov_b32_dpp v128, v50 row_ror:1 row_mask:0xf bank_mask:0xf
	v_mov_b32_dpp v129, v51 row_ror:1 row_mask:0xf bank_mask:0xf
	v_mov_b32_dpp v130, v52 row_ror:1 row_mask:0xf bank_mask:0xf
	s_nop 0
	s_nop 0
	s_nop 0
	v_rcp_f32_e32 v60, v60
	v_rcp_f32_e32 v61, v61
	v_mov_b32_dpp v131, v53 row_ror:1 row_mask:0xf bank_mask:0xf
	v_mov_b32_dpp v132, v50 row_ror:2 row_mask:0xf bank_mask:0xf
	v_mov_b32_dpp v133, v51 row_ror:2 row_mask:0xf bank_mask:0xf
	s_nop 0
	s_nop 0
	v_cndmask_b32_e64 v118, v130, v111, s[6:7]
	v_cndmask_b32_e64 v111, v129, v108, s[6:7]
	v_cndmask_b32_e64 v110, v128, v65, s[6:7]
	v_pk_fma_f32 v[50:51], v[50:51], v[70:71], v[94:95]
	v_mov_b32_dpp v134, v52 row_ror:2 row_mask:0xf bank_mask:0xf
	v_mov_b32_dpp v135, v53 row_ror:2 row_mask:0xf bank_mask:0xf
	v_cndmask_b32_e64 v119, v131, v113, s[6:7]
	v_cndmask_b32_e64 v113, v112, v133, s[10:11]
	v_cndmask_b32_e64 v112, v109, v132, s[10:11]
	v_pk_fma_f32 v[52:53], v[52:53], v[72:73], v[96:97]
	v_pk_fma_f32 v[50:51], v[74:75], v[110:111], v[50:51]
	v_cndmask_b32_e64 v65, v115, v135, s[10:11]
	v_cndmask_b32_e64 v64, v114, v134, s[10:11]
	v_pk_fma_f32 v[52:53], v[76:77], v[118:119], v[52:53]
	v_pk_fma_f32 v[50:51], v[66:67], v[112:113], v[50:51]
	v_pk_mul_f32 v[54:55], v[54:55], v[58:59]
	v_pk_fma_f32 v[52:53], v[68:69], v[64:65], v[52:53]
	v_pk_mul_f32 v[56:57], v[56:57], v[60:61]
	v_pk_mul_f32 v[50:51], v[50:51], v[54:55]
	v_mov_b32_e32 v155, v154
	v_pk_mul_f32 v[52:53], v[52:53], v[56:57]
	v_cvt_pk_bf16_f32 v50, v50, v51
	v_pk_mul_f32 v[46:47], v[46:47], v[154:155]
	v_cvt_pk_bf16_f32 v51, v52, v53
	global_store_dwordx2 v[146:147], v[50:51], off offset:8
	v_mov_b32_e32 v50, v154
	v_mov_b32_e32 v51, v154
	s_nop 0
	s_nop 0
	v_pk_mul_f32 v[48:49], v[48:49], v[50:51]
	v_mov_b32_dpp v99, v46 row_ror:1 row_mask:0xf bank_mask:0xf
	v_mov_b32_dpp v103, v47 row_ror:1 row_mask:0xf bank_mask:0xf
	s_nop 0
	s_nop 0
	s_nop 0
	s_nop 0
	v_mov_b32_dpp v108, v48 row_ror:1 row_mask:0xf bank_mask:0xf
	v_mov_b32_dpp v109, v49 row_ror:1 row_mask:0xf bank_mask:0xf
	v_mov_b32_dpp v110, v46 row_ror:2 row_mask:0xf bank_mask:0xf
	v_mov_b32_dpp v111, v47 row_ror:2 row_mask:0xf bank_mask:0xf
	s_nop 0
	s_nop 0
	v_cndmask_b32_e64 v53, v103, v121, s[6:7]
	v_cndmask_b32_e64 v52, v99, v120, s[6:7]
	v_pk_fma_f32 v[46:47], v[46:47], v[86:87], v[90:91]
	v_pk_mul_f32 v[44:45], v[44:45], v[50:51]
	v_mov_b32_dpp v112, v48 row_ror:2 row_mask:0xf bank_mask:0xf
	v_mov_b32_dpp v113, v49 row_ror:2 row_mask:0xf bank_mask:0xf
	v_cndmask_b32_e64 v51, v109, v123, s[6:7]
	v_cndmask_b32_e64 v50, v108, v122, s[6:7]
	v_cndmask_b32_e64 v57, v125, v111, s[10:11]
	v_cndmask_b32_e64 v56, v124, v110, s[10:11]
	v_pk_fma_f32 v[48:49], v[48:49], v[88:89], v[92:93]
	v_pk_fma_f32 v[46:47], v[82:83], v[52:53], v[46:47]
	v_cndmask_b32_e64 v55, v127, v113, s[10:11]
	v_cndmask_b32_e64 v54, v126, v112, s[10:11]
	v_pk_fma_f32 v[48:49], v[84:85], v[50:51], v[48:49]
	v_pk_fma_f32 v[46:47], v[78:79], v[56:57], v[46:47]
	v_pk_fma_f32 v[48:49], v[80:81], v[54:55], v[48:49]
	v_mul_f32_e32 v50, v46, v46
	v_mul_f32_e32 v51, v47, v47
	v_fmamk_f32 v50, v50, 0xbdd2d3e8, v196
	v_fmamk_f32 v51, v51, 0xbdd2d3e8, v196
	v_mul_f32_e32 v52, v48, v48
	v_mul_f32_e32 v53, v49, v49
	v_mul_f32_e32 v50, v46, v50
	v_mul_f32_e32 v51, v47, v51
	v_fmamk_f32 v52, v52, 0xbdd2d3e8, v196
	v_fmamk_f32 v53, v53, 0xbdd2d3e8, v196
	v_exp_f32_e32 v50, v50
	v_exp_f32_e32 v51, v51
	v_mul_f32_e32 v52, v48, v52
; __device__ __forceinline__ unsigned cvt_pk_bf16(float lo, float hi) { unsigned r; asm volatile("v_cvt_pk_bf16_f32 %0, %1, %2" : "=v"(r) : "v"(lo), "v"(hi)); return r; }
; __device__ __forceinline__ f32x4 gelu4(f32x4 v) { return (f32x4){gelu_t(v[0]), gelu_t(v[1]), gelu_t(v[2]), gelu_t(v[3])}; }
; template <int CTRL> __device__ __forceinline__ f32x4 dpp4(f32x4 v) { return (f32x4){dpp_f<CTRL>(v[0]), dpp_f<CTRL>(v[1]), dpp_f<CTRL>(v[2]), dpp_f<CTRL>(v[3])}; }
;     __device__ __forceinline__ void operator()(const f32x4 (&acc)[2][2][4][2], const Unit& u, int wr, int wc, int fr, int fq) const {
;     ...
;                     for (int m = 0; m < 4; ++m) {
;                         const f32x4 g = acc[ai][0][m][n] * rs[ai][m], v = acc[ai][1][m][n] * rs[ai][m];
;                         const f32x4 g1 = dpp4<0x121>(g), g2 = dpp4<0x122>(g), v1 = dpp4<0x121>(v), v2 = dpp4<0x122>(v);
;                         const f32x4 gp1 = (fr >= 1) ? g1 : pg1, gp2 = (fr >= 2) ? g2 : pg2, vp1 = (fr >= 1) ? v1 : pv1, vp2 = (fr >= 2) ? v2 : pv2;
;                         const f32x4 cgt = bg + wg0 * g + wg1 * gp1 + wg2 * gp2, cvl = bv + wv0 * v + wv1 * vp1 + wv2 * vp2;
;                         const f32x4 o = gelu4(cgt) * cvl;
;                         typedef unsigned u32x2e __attribute__((ext_vector_type(2)));
;                         u32x2e w; w.x = cvt_pk_bf16(o[0], o[1]); w.y = cvt_pk_bf16(o[2], o[3]);
;                         if (!(m == 0 && fr < 2)) *(u32x2e*)((bf16_t*)O + (size_t)(row0 + ai * HALF + m * 16) * DFFc + c) = w;
;                         pg1 = g1; pg2 = g2; pv1 = v1; pv2 = v2;
	v_mul_f32_e32 v53, v49, v53
	v_exp_f32_e32 v52, v52
	v_exp_f32_e32 v53, v53
	v_add_f32_e32 v50, 1.0, v50
	v_add_f32_e32 v51, 1.0, v51
	v_pk_mul_f32 v[42:43], v[42:43], v[154:155]
	s_nop 0
	s_nop 0
	v_rcp_f32_e32 v50, v50
	v_add_f32_e32 v52, 1.0, v52
	v_add_f32_e32 v53, 1.0, v53
	v_rcp_f32_e32 v51, v51
	v_mov_b32_dpp v114, v42 row_ror:1 row_mask:0xf bank_mask:0xf
	v_mov_b32_dpp v115, v43 row_ror:1 row_mask:0xf bank_mask:0xf
	s_nop 0
	s_nop 0
	s_nop 0
	s_nop 0
	v_rcp_f32_e32 v52, v52
	v_rcp_f32_e32 v53, v53
	v_mov_b32_dpp v116, v44 row_ror:1 row_mask:0xf bank_mask:0xf
	v_mov_b32_dpp v117, v45 row_ror:1 row_mask:0xf bank_mask:0xf
	v_mov_b32_dpp v118, v42 row_ror:2 row_mask:0xf bank_mask:0xf
	v_mov_b32_dpp v119, v43 row_ror:2 row_mask:0xf bank_mask:0xf
	s_nop 0
	s_nop 0
	v_cndmask_b32_e64 v61, v115, v129, s[6:7]
	v_cndmask_b32_e64 v60, v114, v128, s[6:7]
	v_pk_fma_f32 v[42:43], v[42:43], v[70:71], v[94:95]
	v_mov_b32_dpp v136, v44 row_ror:2 row_mask:0xf bank_mask:0xf
	v_mov_b32_dpp v137, v45 row_ror:2 row_mask:0xf bank_mask:0xf
	v_cndmask_b32_e64 v59, v117, v131, s[6:7]
	v_cndmask_b32_e64 v58, v116, v130, s[6:7]
	v_cndmask_b32_e64 v65, v133, v119, s[10:11]
	v_cndmask_b32_e64 v64, v132, v118, s[10:11]
	v_pk_fma_f32 v[44:45], v[44:45], v[72:73], v[96:97]
	v_pk_fma_f32 v[42:43], v[74:75], v[60:61], v[42:43]
	v_cndmask_b32_e64 v63, v135, v137, s[10:11]
	v_cndmask_b32_e64 v62, v134, v136, s[10:11]
	v_pk_fma_f32 v[44:45], v[76:77], v[58:59], v[44:45]
	v_pk_fma_f32 v[42:43], v[66:67], v[64:65], v[42:43]
	v_pk_mul_f32 v[46:47], v[46:47], v[50:51]
	v_pk_fma_f32 v[44:45], v[68:69], v[62:63], v[44:45]
	v_pk_mul_f32 v[48:49], v[48:49], v[52:53]
	v_pk_mul_f32 v[42:43], v[42:43], v[46:47]
	v_mov_b32_e32 v185, v184
	v_pk_mul_f32 v[44:45], v[44:45], v[48:49]
	v_cvt_pk_bf16_f32 v42, v42, v43
	v_pk_mul_f32 v[38:39], v[38:39], v[184:185]
	v_cvt_pk_bf16_f32 v43, v44, v45
	global_store_dwordx2 v[138:139], v[42:43], off offset:8
	v_mov_b32_e32 v42, v184
	v_mov_b32_e32 v43, v184
	s_nop 0
	s_nop 0
	v_pk_mul_f32 v[40:41], v[40:41], v[42:43]
	v_pk_mul_f32 v[36:37], v[36:37], v[42:43]
	v_mov_b32_dpp v44, v38 row_ror:1 row_mask:0xf bank_mask:0xf
	v_mov_b32_dpp v45, v39 row_ror:1 row_mask:0xf bank_mask:0xf
	s_nop 0
	s_nop 0
	s_nop 0
	s_nop 0
	v_mov_b32_dpp v42, v40 row_ror:1 row_mask:0xf bank_mask:0xf
	v_mov_b32_dpp v43, v41 row_ror:1 row_mask:0xf bank_mask:0xf
	v_mov_b32_dpp v48, v38 row_ror:2 row_mask:0xf bank_mask:0xf
	v_mov_b32_dpp v49, v39 row_ror:2 row_mask:0xf bank_mask:0xf
	s_nop 0
	s_nop 0
	v_cndmask_b32_e64 v45, v45, v103, s[6:7]
	v_cndmask_b32_e64 v44, v44, v99, s[6:7]
	v_pk_fma_f32 v[38:39], v[38:39], v[86:87], v[90:91]
	v_mov_b32_dpp v46, v40 row_ror:2 row_mask:0xf bank_mask:0xf
	v_mov_b32_dpp v47, v41 row_ror:2 row_mask:0xf bank_mask:0xf
	v_cndmask_b32_e64 v43, v43, v109, s[6:7]
	v_cndmask_b32_e64 v42, v42, v108, s[6:7]
	v_cndmask_b32_e64 v49, v111, v49, s[10:11]
	v_cndmask_b32_e64 v48, v110, v48, s[10:11]
	v_pk_fma_f32 v[40:41], v[40:41], v[88:89], v[92:93]
	v_pk_fma_f32 v[38:39], v[82:83], v[44:45], v[38:39]
	v_cndmask_b32_e64 v47, v113, v47, s[10:11]
	v_cndmask_b32_e64 v46, v112, v46, s[10:11]
	v_pk_fma_f32 v[40:41], v[84:85], v[42:43], v[40:41]
	v_pk_fma_f32 v[38:39], v[78:79], v[48:49], v[38:39]
	v_pk_fma_f32 v[40:41], v[80:81], v[46:47], v[40:41]
	v_mul_f32_e32 v42, v38, v38
	v_mul_f32_e32 v43, v39, v39
	v_fmamk_f32 v42, v42, 0xbdd2d3e8, v196
	v_fmamk_f32 v43, v43, 0xbdd2d3e8, v196
	v_mul_f32_e32 v44, v40, v40
	v_mul_f32_e32 v45, v41, v41
	v_mul_f32_e32 v42, v38, v42
	v_mul_f32_e32 v43, v39, v43
	v_fmamk_f32 v44, v44, 0xbdd2d3e8, v196
	v_fmamk_f32 v45, v45, 0xbdd2d3e8, v196
	v_exp_f32_e32 v42, v42
	v_exp_f32_e32 v43, v43
	v_mul_f32_e32 v44, v40, v44
	v_mul_f32_e32 v45, v41, v45
	v_exp_f32_e32 v44, v44
	v_exp_f32_e32 v45, v45
	v_add_f32_e32 v42, 1.0, v42
	v_add_f32_e32 v43, 1.0, v43
	v_pk_mul_f32 v[34:35], v[34:35], v[184:185]
	s_nop 0
	s_nop 0
	v_rcp_f32_e32 v42, v42
	v_add_f32_e32 v44, 1.0, v44
	v_add_f32_e32 v45, 1.0, v45
	v_rcp_f32_e32 v43, v43
	v_mov_b32_dpp v52, v34 row_ror:1 row_mask:0xf bank_mask:0xf
	v_mov_b32_dpp v53, v35 row_ror:1 row_mask:0xf bank_mask:0xf
	s_nop 0
	s_nop 0
	s_nop 0
	s_nop 0
	v_rcp_f32_e32 v44, v44
	v_rcp_f32_e32 v45, v45
	v_mov_b32_dpp v50, v36 row_ror:1 row_mask:0xf bank_mask:0xf
	v_mov_b32_dpp v51, v37 row_ror:1 row_mask:0xf bank_mask:0xf
	v_mov_b32_dpp v56, v34 row_ror:2 row_mask:0xf bank_mask:0xf
	v_mov_b32_dpp v57, v35 row_ror:2 row_mask:0xf bank_mask:0xf
	s_nop 0
	s_nop 0
	v_cndmask_b32_e64 v53, v53, v115, s[6:7]
	v_cndmask_b32_e64 v52, v52, v114, s[6:7]
	v_pk_fma_f32 v[34:35], v[34:35], v[70:71], v[94:95]
	v_mov_b32_dpp v54, v36 row_ror:2 row_mask:0xf bank_mask:0xf
	v_mov_b32_dpp v55, v37 row_ror:2 row_mask:0xf bank_mask:0xf
	v_cndmask_b32_e64 v51, v51, v117, s[6:7]
	v_cndmask_b32_e64 v50, v50, v116, s[6:7]
	v_cndmask_b32_e64 v57, v119, v57, s[10:11]
	v_cndmask_b32_e64 v56, v118, v56, s[10:11]
	v_pk_fma_f32 v[36:37], v[36:37], v[72:73], v[96:97]
	v_pk_fma_f32 v[34:35], v[74:75], v[52:53], v[34:35]
	v_cndmask_b32_e64 v55, v137, v55, s[10:11]
	v_cndmask_b32_e64 v54, v136, v54, s[10:11]
	v_pk_fma_f32 v[36:37], v[76:77], v[50:51], v[36:37]
	v_pk_fma_f32 v[34:35], v[66:67], v[56:57], v[34:35]
	v_pk_mul_f32 v[38:39], v[38:39], v[42:43]
	v_pk_fma_f32 v[36:37], v[68:69], v[54:55], v[36:37]
	v_pk_mul_f32 v[40:41], v[40:41], v[44:45]
	v_pk_mul_f32 v[34:35], v[34:35], v[38:39]
	v_pk_mul_f32 v[36:37], v[36:37], v[40:41]
	v_cvt_pk_bf16_f32 v34, v34, v35
	v_mov_b32_e32 v183, v182
	v_cvt_pk_bf16_f32 v35, v36, v37
	global_store_dwordx2 v[100:101], v[34:35], off offset:8
	v_mov_b32_e32 v34, v182
	v_mov_b32_e32 v35, v182
; __device__ __forceinline__ unsigned cvt_pk_bf16(float lo, float hi) { unsigned r; asm volatile("v_cvt_pk_bf16_f32 %0, %1, %2" : "=v"(r) : "v"(lo), "v"(hi)); return r; }
; __device__ __forceinline__ f32x4 gelu4(f32x4 v) { return (f32x4){gelu_t(v[0]), gelu_t(v[1]), gelu_t(v[2]), gelu_t(v[3])}; }
; template <int CTRL> __device__ __forceinline__ f32x4 dpp4(f32x4 v) { return (f32x4){dpp_f<CTRL>(v[0]), dpp_f<CTRL>(v[1]), dpp_f<CTRL>(v[2]), dpp_f<CTRL>(v[3])}; }
;     __device__ __forceinline__ void operator()(const f32x4 (&acc)[2][2][4][2], const Unit& u, int wr, int wc, int fr, int fq) const {
;     ...
;                     for (int m = 0; m < 4; ++m) {
;                         const f32x4 g = acc[ai][0][m][n] * rs[ai][m], v = acc[ai][1][m][n] * rs[ai][m];
;                         const f32x4 g1 = dpp4<0x121>(g), g2 = dpp4<0x122>(g), v1 = dpp4<0x121>(v), v2 = dpp4<0x122>(v);
;                         const f32x4 gp1 = (fr >= 1) ? g1 : pg1, gp2 = (fr >= 2) ? g2 : pg2, vp1 = (fr >= 1) ? v1 : pv1, vp2 = (fr >= 2) ? v2 : pv2;
;                         const f32x4 cgt = bg + wg0 * g + wg1 * gp1 + wg2 * gp2, cvl = bv + wv0 * v + wv1 * vp1 + wv2 * vp2;
;                         const f32x4 o = gelu4(cgt) * cvl;
;                         typedef unsigned u32x2e __attribute__((ext_vector_type(2)));
;                         u32x2e w; w.x = cvt_pk_bf16(o[0], o[1]); w.y = cvt_pk_bf16(o[2], o[3]);
;                         if (!(m == 0 && fr < 2)) *(u32x2e*)((bf16_t*)O + (size_t)(row0 + ai * HALF + m * 16) * DFFc + c) = w;
;                         pg1 = g1; pg2 = g2; pv1 = v1; pv2 = v2;
	v_pk_mul_f32 v[46:47], v[30:31], v[182:183]
	v_pk_mul_f32 v[48:49], v[28:29], v[34:35]
	s_nop 0
	s_nop 0
	v_pk_mul_f32 v[44:45], v[32:33], v[34:35]
	v_mov_b32_dpp v28, v46 row_ror:1 row_mask:0xf bank_mask:0xf
	v_mov_b32_dpp v29, v47 row_ror:1 row_mask:0xf bank_mask:0xf
	s_nop 0
	s_nop 0
	s_nop 0
	s_nop 0
	v_mov_b32_dpp v31, v44 row_ror:1 row_mask:0xf bank_mask:0xf
	v_mov_b32_dpp v34, v45 row_ror:1 row_mask:0xf bank_mask:0xf
	v_mov_b32_dpp v30, v46 row_ror:2 row_mask:0xf bank_mask:0xf
	v_mov_b32_dpp v32, v47 row_ror:2 row_mask:0xf bank_mask:0xf
	s_nop 0
	s_nop 0
	v_cndmask_b32_e64 v53, v29, 0, s[6:7]
	v_cndmask_b32_e64 v52, v28, 0, s[6:7]
	v_pk_fma_f32 v[46:47], v[46:47], v[86:87], v[90:91]
	v_mov_b32_dpp v35, v44 row_ror:2 row_mask:0xf bank_mask:0xf
	v_mov_b32_dpp v38, v45 row_ror:2 row_mask:0xf bank_mask:0xf
	v_cndmask_b32_e64 v51, v34, 0, s[6:7]
	v_cndmask_b32_e64 v50, v31, 0, s[6:7]
	v_cndmask_b32_e64 v57, 0, v32, s[10:11]
	v_cndmask_b32_e64 v56, 0, v30, s[10:11]
	v_pk_fma_f32 v[44:45], v[44:45], v[88:89], v[92:93]
	v_pk_fma_f32 v[46:47], v[82:83], v[52:53], v[46:47]
	v_cndmask_b32_e64 v55, 0, v38, s[10:11]
	v_cndmask_b32_e64 v54, 0, v35, s[10:11]
	v_pk_fma_f32 v[44:45], v[84:85], v[50:51], v[44:45]
	v_pk_fma_f32 v[46:47], v[78:79], v[56:57], v[46:47]
	v_pk_fma_f32 v[44:45], v[80:81], v[54:55], v[44:45]
	v_mul_f32_e32 v50, v46, v46
	v_mul_f32_e32 v51, v47, v47
	v_fmamk_f32 v50, v50, 0xbdd2d3e8, v196
	v_fmamk_f32 v51, v51, 0xbdd2d3e8, v196
	v_mul_f32_e32 v52, v44, v44
	v_mul_f32_e32 v53, v45, v45
	v_mul_f32_e32 v50, v46, v50
	v_mul_f32_e32 v51, v47, v51
	v_fmamk_f32 v52, v52, 0xbdd2d3e8, v196
	v_fmamk_f32 v53, v53, 0xbdd2d3e8, v196
	v_exp_f32_e32 v50, v50
	v_exp_f32_e32 v51, v51
	v_mul_f32_e32 v52, v44, v52
	v_mul_f32_e32 v53, v45, v53
	v_exp_f32_e32 v52, v52
	v_exp_f32_e32 v53, v53
	v_add_f32_e32 v50, 1.0, v50
	v_add_f32_e32 v51, 1.0, v51
	v_pk_mul_f32 v[26:27], v[26:27], v[182:183]
	s_nop 0
	s_nop 0
	v_rcp_f32_e32 v50, v50
	v_add_f32_e32 v52, 1.0, v52
	v_add_f32_e32 v53, 1.0, v53
	v_rcp_f32_e32 v51, v51
	v_mov_b32_dpp v33, v26 row_ror:1 row_mask:0xf bank_mask:0xf
	v_mov_b32_dpp v36, v27 row_ror:1 row_mask:0xf bank_mask:0xf
	s_nop 0
	s_nop 0
	s_nop 0
	s_nop 0
	v_rcp_f32_e32 v52, v52
	v_rcp_f32_e32 v53, v53
	v_mov_b32_dpp v39, v48 row_ror:1 row_mask:0xf bank_mask:0xf
	v_mov_b32_dpp v41, v49 row_ror:1 row_mask:0xf bank_mask:0xf
	v_mov_b32_dpp v37, v26 row_ror:2 row_mask:0xf bank_mask:0xf
	v_mov_b32_dpp v40, v27 row_ror:2 row_mask:0xf bank_mask:0xf
	s_nop 0
	s_nop 0
	v_cndmask_b32_e64 v61, v36, 0, s[6:7]
	v_cndmask_b32_e64 v60, v33, 0, s[6:7]
	v_pk_fma_f32 v[26:27], v[26:27], v[70:71], v[94:95]
	v_mov_b32_dpp v42, v48 row_ror:2 row_mask:0xf bank_mask:0xf
	v_mov_b32_dpp v43, v49 row_ror:2 row_mask:0xf bank_mask:0xf
	v_cndmask_b32_e64 v59, v41, 0, s[6:7]
	v_cndmask_b32_e64 v58, v39, 0, s[6:7]
	v_cndmask_b32_e64 v65, 0, v40, s[10:11]
	v_cndmask_b32_e64 v64, 0, v37, s[10:11]
	v_pk_fma_f32 v[48:49], v[48:49], v[72:73], v[96:97]
	v_pk_fma_f32 v[26:27], v[74:75], v[60:61], v[26:27]
	v_cndmask_b32_e64 v63, 0, v43, s[10:11]
	v_cndmask_b32_e64 v62, 0, v42, s[10:11]
	v_pk_fma_f32 v[48:49], v[76:77], v[58:59], v[48:49]
	v_pk_fma_f32 v[26:27], v[66:67], v[64:65], v[26:27]
	v_pk_mul_f32 v[46:47], v[46:47], v[50:51]
	v_pk_fma_f32 v[48:49], v[68:69], v[62:63], v[48:49]
	v_pk_mul_f32 v[44:45], v[44:45], v[52:53]
	v_pk_mul_f32 v[26:27], v[26:27], v[46:47]
	v_pk_mul_f32 v[44:45], v[48:49], v[44:45]
	v_cvt_pk_bf16_f32 v26, v26, v27
	s_nop 0
	v_cvt_pk_bf16_f32 v27, v44, v45
	s_and_saveexec_b64 s[48:49], s[10:11]
	s_cbranch_execz .LBB0_62
	v_mov_b64_e32 v[44:45], s[68:69]
	v_mad_i64_i32 v[44:45], s[50:51], v179, s76, v[44:45]
	v_lshl_add_u64 v[44:45], v[180:181], 1, v[44:45]
	global_store_dwordx2 v[44:45], v[26:27], off offset:8
.LBB0_62:
	s_or_b64 exec, exec, s[48:49]
	v_mov_b32_e32 v103, v102
	v_mov_b32_e32 v26, v102
	v_mov_b32_e32 v27, v102
	v_pk_mul_f32 v[22:23], v[22:23], v[102:103]
	s_nop 0
	s_nop 0
	v_pk_mul_f32 v[24:25], v[24:25], v[26:27]
	v_mov_b32_dpp v46, v22 row_ror:1 row_mask:0xf bank_mask:0xf
	v_mov_b32_dpp v47, v23 row_ror:1 row_mask:0xf bank_mask:0xf
	s_nop 0
	s_nop 0
	s_nop 0
	s_nop 0
	v_mov_b32_dpp v48, v24 row_ror:1 row_mask:0xf bank_mask:0xf
	v_mov_b32_dpp v49, v25 row_ror:1 row_mask:0xf bank_mask:0xf
	v_mov_b32_dpp v50, v22 row_ror:2 row_mask:0xf bank_mask:0xf
	v_mov_b32_dpp v51, v23 row_ror:2 row_mask:0xf bank_mask:0xf
	s_nop 0
	s_nop 0
	v_cndmask_b32_e64 v29, v47, v29, s[6:7]
	v_cndmask_b32_e64 v28, v46, v28, s[6:7]
	v_pk_fma_f32 v[22:23], v[22:23], v[86:87], v[90:91]
	v_pk_mul_f32 v[20:21], v[20:21], v[26:27]
	v_mov_b32_dpp v52, v24 row_ror:2 row_mask:0xf bank_mask:0xf
	v_mov_b32_dpp v53, v25 row_ror:2 row_mask:0xf bank_mask:0xf
	v_cndmask_b32_e64 v27, v49, v34, s[6:7]
	v_cndmask_b32_e64 v26, v48, v31, s[6:7]
	v_cndmask_b32_e64 v31, v32, v51, s[10:11]
	v_cndmask_b32_e64 v30, v30, v50, s[10:11]
	v_pk_fma_f32 v[24:25], v[24:25], v[88:89], v[92:93]
	v_pk_fma_f32 v[22:23], v[82:83], v[28:29], v[22:23]
	v_cndmask_b32_e64 v45, v38, v53, s[10:11]
	v_cndmask_b32_e64 v44, v35, v52, s[10:11]
	v_pk_fma_f32 v[24:25], v[84:85], v[26:27], v[24:25]
	v_pk_fma_f32 v[22:23], v[78:79], v[30:31], v[22:23]
	v_pk_fma_f32 v[24:25], v[80:81], v[44:45], v[24:25]
	v_mul_f32_e32 v26, v22, v22
	v_mul_f32_e32 v27, v23, v23
	v_fmamk_f32 v26, v26, 0xbdd2d3e8, v196
	v_fmamk_f32 v27, v27, 0xbdd2d3e8, v196
	v_mul_f32_e32 v28, v24, v24
	v_mul_f32_e32 v29, v25, v25
	v_mul_f32_e32 v26, v22, v26
	v_mul_f32_e32 v27, v23, v27
	v_fmamk_f32 v28, v28, 0xbdd2d3e8, v196
	v_fmamk_f32 v29, v29, 0xbdd2d3e8, v196
	v_exp_f32_e32 v26, v26
	v_exp_f32_e32 v27, v27
	v_mul_f32_e32 v28, v24, v28
; __device__ __forceinline__ unsigned cvt_pk_bf16(float lo, float hi) { unsigned r; asm volatile("v_cvt_pk_bf16_f32 %0, %1, %2" : "=v"(r) : "v"(lo), "v"(hi)); return r; }
; __device__ __forceinline__ f32x4 gelu4(f32x4 v) { return (f32x4){gelu_t(v[0]), gelu_t(v[1]), gelu_t(v[2]), gelu_t(v[3])}; }
; template <int CTRL> __device__ __forceinline__ f32x4 dpp4(f32x4 v) { return (f32x4){dpp_f<CTRL>(v[0]), dpp_f<CTRL>(v[1]), dpp_f<CTRL>(v[2]), dpp_f<CTRL>(v[3])}; }
;     __device__ __forceinline__ void operator()(const f32x4 (&acc)[2][2][4][2], const Unit& u, int wr, int wc, int fr, int fq) const {
;     ...
;                     for (int m = 0; m < 4; ++m) {
;                         const f32x4 g = acc[ai][0][m][n] * rs[ai][m], v = acc[ai][1][m][n] * rs[ai][m];
;                         const f32x4 g1 = dpp4<0x121>(g), g2 = dpp4<0x122>(g), v1 = dpp4<0x121>(v), v2 = dpp4<0x122>(v);
;                         const f32x4 gp1 = (fr >= 1) ? g1 : pg1, gp2 = (fr >= 2) ? g2 : pg2, vp1 = (fr >= 1) ? v1 : pv1, vp2 = (fr >= 2) ? v2 : pv2;
;                         const f32x4 cgt = bg + wg0 * g + wg1 * gp1 + wg2 * gp2, cvl = bv + wv0 * v + wv1 * vp1 + wv2 * vp2;
;                         const f32x4 o = gelu4(cgt) * cvl;
;                         typedef unsigned u32x2e __attribute__((ext_vector_type(2)));
;                         u32x2e w; w.x = cvt_pk_bf16(o[0], o[1]); w.y = cvt_pk_bf16(o[2], o[3]);
;                         if (!(m == 0 && fr < 2)) *(u32x2e*)((bf16_t*)O + (size_t)(row0 + ai * HALF + m * 16) * DFFc + c) = w;
;                         pg1 = g1; pg2 = g2; pv1 = v1; pv2 = v2;
	v_mul_f32_e32 v29, v25, v29
	v_exp_f32_e32 v28, v28
	v_exp_f32_e32 v29, v29
	v_add_f32_e32 v26, 1.0, v26
	v_add_f32_e32 v27, 1.0, v27
	v_pk_mul_f32 v[18:19], v[18:19], v[102:103]
	s_nop 0
	s_nop 0
	s_nop 0
	v_rcp_f32_e32 v26, v26
	v_add_f32_e32 v28, 1.0, v28
	v_add_f32_e32 v29, 1.0, v29
	v_rcp_f32_e32 v27, v27
	v_mov_b32_dpp v54, v18 row_ror:1 row_mask:0xf bank_mask:0xf
	v_mov_b32_dpp v55, v19 row_ror:1 row_mask:0xf bank_mask:0xf
	v_mov_b32_dpp v56, v20 row_ror:1 row_mask:0xf bank_mask:0xf
	s_nop 0
	s_nop 0
	s_nop 0
	v_rcp_f32_e32 v28, v28
	v_rcp_f32_e32 v29, v29
	v_mov_b32_dpp v57, v21 row_ror:1 row_mask:0xf bank_mask:0xf
	v_mov_b32_dpp v58, v18 row_ror:2 row_mask:0xf bank_mask:0xf
	v_mov_b32_dpp v59, v19 row_ror:2 row_mask:0xf bank_mask:0xf
	s_nop 0
	s_nop 0
	v_cndmask_b32_e64 v34, v56, v39, s[6:7]
	v_cndmask_b32_e64 v39, v55, v36, s[6:7]
	v_cndmask_b32_e64 v38, v54, v33, s[6:7]
	v_pk_fma_f32 v[18:19], v[18:19], v[70:71], v[94:95]
	v_mov_b32_dpp v60, v20 row_ror:2 row_mask:0xf bank_mask:0xf
	v_mov_b32_dpp v61, v21 row_ror:2 row_mask:0xf bank_mask:0xf
	v_cndmask_b32_e64 v35, v57, v41, s[6:7]
	v_cndmask_b32_e64 v41, v40, v59, s[10:11]
	v_cndmask_b32_e64 v40, v37, v58, s[10:11]
	v_pk_fma_f32 v[20:21], v[20:21], v[72:73], v[96:97]
	v_pk_fma_f32 v[18:19], v[74:75], v[38:39], v[18:19]
	v_cndmask_b32_e64 v33, v43, v61, s[10:11]
	v_cndmask_b32_e64 v32, v42, v60, s[10:11]
	v_pk_fma_f32 v[20:21], v[76:77], v[34:35], v[20:21]
	v_pk_fma_f32 v[18:19], v[66:67], v[40:41], v[18:19]
	v_pk_mul_f32 v[22:23], v[22:23], v[26:27]
	v_pk_fma_f32 v[20:21], v[68:69], v[32:33], v[20:21]
	v_pk_mul_f32 v[24:25], v[24:25], v[28:29]
	v_pk_mul_f32 v[18:19], v[18:19], v[22:23]
	v_mov_b32_e32 v99, v98
	v_pk_mul_f32 v[20:21], v[20:21], v[24:25]
	v_cvt_pk_bf16_f32 v18, v18, v19
	v_pk_mul_f32 v[14:15], v[14:15], v[98:99]
	v_cvt_pk_bf16_f32 v19, v20, v21
	global_store_dwordx2 v[104:105], v[18:19], off offset:8
	v_mov_b32_e32 v18, v98
	v_mov_b32_e32 v19, v98
	s_nop 0
	s_nop 0
	v_pk_mul_f32 v[16:17], v[16:17], v[18:19]
	v_mov_b32_dpp v34, v14 row_ror:1 row_mask:0xf bank_mask:0xf
	v_mov_b32_dpp v35, v15 row_ror:1 row_mask:0xf bank_mask:0xf
	s_nop 0
	s_nop 0
	s_nop 0
	s_nop 0
	v_mov_b32_dpp v36, v16 row_ror:1 row_mask:0xf bank_mask:0xf
	v_mov_b32_dpp v37, v17 row_ror:1 row_mask:0xf bank_mask:0xf
	v_mov_b32_dpp v38, v14 row_ror:2 row_mask:0xf bank_mask:0xf
	v_mov_b32_dpp v39, v15 row_ror:2 row_mask:0xf bank_mask:0xf
	s_nop 0
	s_nop 0
	v_cndmask_b32_e64 v21, v35, v47, s[6:7]
	v_cndmask_b32_e64 v20, v34, v46, s[6:7]
	v_pk_fma_f32 v[14:15], v[14:15], v[86:87], v[90:91]
	v_pk_mul_f32 v[12:13], v[12:13], v[18:19]
	v_mov_b32_dpp v40, v16 row_ror:2 row_mask:0xf bank_mask:0xf
	v_mov_b32_dpp v41, v17 row_ror:2 row_mask:0xf bank_mask:0xf
	v_cndmask_b32_e64 v19, v37, v49, s[6:7]
	v_cndmask_b32_e64 v18, v36, v48, s[6:7]
	v_cndmask_b32_e64 v25, v51, v39, s[10:11]
	v_cndmask_b32_e64 v24, v50, v38, s[10:11]
	v_pk_fma_f32 v[16:17], v[16:17], v[88:89], v[92:93]
	v_pk_fma_f32 v[14:15], v[82:83], v[20:21], v[14:15]
	v_cndmask_b32_e64 v23, v53, v41, s[10:11]
	v_cndmask_b32_e64 v22, v52, v40, s[10:11]
	v_pk_fma_f32 v[16:17], v[84:85], v[18:19], v[16:17]
	v_pk_fma_f32 v[14:15], v[78:79], v[24:25], v[14:15]
	v_pk_fma_f32 v[16:17], v[80:81], v[22:23], v[16:17]
	v_mul_f32_e32 v18, v14, v14
	v_mul_f32_e32 v19, v15, v15
	v_fmamk_f32 v18, v18, 0xbdd2d3e8, v196
	v_fmamk_f32 v19, v19, 0xbdd2d3e8, v196
	v_mul_f32_e32 v20, v16, v16
	v_mul_f32_e32 v21, v17, v17
	v_mul_f32_e32 v18, v14, v18
	v_mul_f32_e32 v19, v15, v19
	v_fmamk_f32 v20, v20, 0xbdd2d3e8, v196
	v_fmamk_f32 v21, v21, 0xbdd2d3e8, v196
	v_exp_f32_e32 v18, v18
	v_exp_f32_e32 v19, v19
	v_mul_f32_e32 v20, v16, v20
	v_mul_f32_e32 v21, v17, v21
	v_exp_f32_e32 v20, v20
	v_exp_f32_e32 v21, v21
	v_add_f32_e32 v18, 1.0, v18
	v_add_f32_e32 v19, 1.0, v19
	v_pk_mul_f32 v[10:11], v[10:11], v[98:99]
	s_nop 0
	s_nop 0
	v_rcp_f32_e32 v18, v18
	v_add_f32_e32 v20, 1.0, v20
	v_add_f32_e32 v21, 1.0, v21
	v_rcp_f32_e32 v19, v19
	v_mov_b32_dpp v42, v10 row_ror:1 row_mask:0xf bank_mask:0xf
	v_mov_b32_dpp v43, v11 row_ror:1 row_mask:0xf bank_mask:0xf
	s_nop 0
	s_nop 0
	s_nop 0
	s_nop 0
	v_rcp_f32_e32 v20, v20
	v_rcp_f32_e32 v21, v21
	v_mov_b32_dpp v44, v12 row_ror:1 row_mask:0xf bank_mask:0xf
	v_mov_b32_dpp v45, v13 row_ror:1 row_mask:0xf bank_mask:0xf
	v_mov_b32_dpp v62, v10 row_ror:2 row_mask:0xf bank_mask:0xf
	v_mov_b32_dpp v63, v11 row_ror:2 row_mask:0xf bank_mask:0xf
	s_nop 0
	s_nop 0
	v_cndmask_b32_e64 v29, v43, v55, s[6:7]
	v_cndmask_b32_e64 v28, v42, v54, s[6:7]
	v_pk_fma_f32 v[10:11], v[10:11], v[70:71], v[94:95]
	v_mov_b32_dpp v64, v12 row_ror:2 row_mask:0xf bank_mask:0xf
; __device__ __forceinline__ unsigned cvt_pk_bf16(float lo, float hi) { unsigned r; asm volatile("v_cvt_pk_bf16_f32 %0, %1, %2" : "=v"(r) : "v"(lo), "v"(hi)); return r; }
; __device__ __forceinline__ f32x4 gelu4(f32x4 v) { return (f32x4){gelu_t(v[0]), gelu_t(v[1]), gelu_t(v[2]), gelu_t(v[3])}; }
; template <int CTRL> __device__ __forceinline__ f32x4 dpp4(f32x4 v) { return (f32x4){dpp_f<CTRL>(v[0]), dpp_f<CTRL>(v[1]), dpp_f<CTRL>(v[2]), dpp_f<CTRL>(v[3])}; }
;     __device__ __forceinline__ void operator()(const f32x4 (&acc)[2][2][4][2], const Unit& u, int wr, int wc, int fr, int fq) const {
;     ...
;                     for (int m = 0; m < 4; ++m) {
;                         const f32x4 g = acc[ai][0][m][n] * rs[ai][m], v = acc[ai][1][m][n] * rs[ai][m];
;                         const f32x4 g1 = dpp4<0x121>(g), g2 = dpp4<0x122>(g), v1 = dpp4<0x121>(v), v2 = dpp4<0x122>(v);
;                         const f32x4 gp1 = (fr >= 1) ? g1 : pg1, gp2 = (fr >= 2) ? g2 : pg2, vp1 = (fr >= 1) ? v1 : pv1, vp2 = (fr >= 2) ? v2 : pv2;
;                         const f32x4 cgt = bg + wg0 * g + wg1 * gp1 + wg2 * gp2, cvl = bv + wv0 * v + wv1 * vp1 + wv2 * vp2;
;                         const f32x4 o = gelu4(cgt) * cvl;
;                         typedef unsigned u32x2e __attribute__((ext_vector_type(2)));
;                         u32x2e w; w.x = cvt_pk_bf16(o[0], o[1]); w.y = cvt_pk_bf16(o[2], o[3]);
;                         if (!(m == 0 && fr < 2)) *(u32x2e*)((bf16_t*)O + (size_t)(row0 + ai * HALF + m * 16) * DFFc + c) = w;
;                         pg1 = g1; pg2 = g2; pv1 = v1; pv2 = v2;
; template <class Epi, class Sched, bool ALIGN_EPI = false, bool SP2 = false>
; __device__ __forceinline__ void gemm_phase(PG8_LAS unsigned char* lds, const Gemm g, const Sched& S, const Epi& E, int wave_in) {
;     ...
;         if constexpr (ALIGN_EPI) { if (wr == 0) PG8_BAR; }
;         if constexpr (!Epi::AFTER_DRAIN) { E(acc, cur, wr, wc, fr, fq); S.done(cur); }
;         if (!has_next) break;
; #pragma unroll
;         for (int a = 0; a < 2; ++a)
; #pragma unroll
;             for (int b = 0; b < 2; ++b)
; #pragma unroll
;                 for (int m = 0; m < 4; ++m)
; #pragma unroll
;                     for (int n = 0; n < 2; ++n) acc[a][b][m][n] = (f32x4){0.f, 0.f, 0.f, 0.f};
;         cur = nxt; cA = nA; cB = nB; ++ui;
;         if constexpr (ALIGN_EPI) { if (wr == 1) PG8_BAR; }
	v_mov_b32_dpp v65, v13 row_ror:2 row_mask:0xf bank_mask:0xf
	v_cndmask_b32_e64 v27, v45, v57, s[6:7]
	v_cndmask_b32_e64 v26, v44, v56, s[6:7]
	v_cndmask_b32_e64 v33, v59, v63, s[10:11]
	v_cndmask_b32_e64 v32, v58, v62, s[10:11]
	v_pk_fma_f32 v[12:13], v[12:13], v[72:73], v[96:97]
	v_pk_fma_f32 v[10:11], v[74:75], v[28:29], v[10:11]
	v_cndmask_b32_e64 v31, v61, v65, s[10:11]
	v_cndmask_b32_e64 v30, v60, v64, s[10:11]
	v_pk_fma_f32 v[12:13], v[76:77], v[26:27], v[12:13]
	v_pk_fma_f32 v[10:11], v[66:67], v[32:33], v[10:11]
	v_pk_mul_f32 v[14:15], v[14:15], v[18:19]
	v_pk_fma_f32 v[12:13], v[68:69], v[30:31], v[12:13]
	v_pk_mul_f32 v[16:17], v[16:17], v[20:21]
	v_pk_mul_f32 v[10:11], v[10:11], v[14:15]
	v_mov_b32_e32 v179, v178
	v_pk_mul_f32 v[12:13], v[12:13], v[16:17]
	v_cvt_pk_bf16_f32 v10, v10, v11
	v_pk_mul_f32 v[6:7], v[6:7], v[178:179]
	v_cvt_pk_bf16_f32 v11, v12, v13
	global_store_dwordx2 v[140:141], v[10:11], off offset:8
	v_mov_b32_e32 v10, v178
	v_mov_b32_e32 v11, v178
	s_nop 0
	s_nop 0
	v_pk_mul_f32 v[8:9], v[8:9], v[10:11]
	v_pk_mul_f32 v[4:5], v[4:5], v[10:11]
	v_mov_b32_dpp v12, v6 row_ror:1 row_mask:0xf bank_mask:0xf
	v_mov_b32_dpp v13, v7 row_ror:1 row_mask:0xf bank_mask:0xf
	s_nop 0
	s_nop 0
	s_nop 0
	s_nop 0
	v_mov_b32_dpp v10, v8 row_ror:1 row_mask:0xf bank_mask:0xf
	v_mov_b32_dpp v11, v9 row_ror:1 row_mask:0xf bank_mask:0xf
	v_mov_b32_dpp v16, v6 row_ror:2 row_mask:0xf bank_mask:0xf
	v_mov_b32_dpp v17, v7 row_ror:2 row_mask:0xf bank_mask:0xf
	s_nop 0
	s_nop 0
	v_cndmask_b32_e64 v13, v13, v35, s[6:7]
	v_cndmask_b32_e64 v12, v12, v34, s[6:7]
	v_pk_fma_f32 v[6:7], v[6:7], v[86:87], v[90:91]
	v_mov_b32_dpp v14, v8 row_ror:2 row_mask:0xf bank_mask:0xf
	v_mov_b32_dpp v15, v9 row_ror:2 row_mask:0xf bank_mask:0xf
	v_cndmask_b32_e64 v11, v11, v37, s[6:7]
	v_cndmask_b32_e64 v10, v10, v36, s[6:7]
	v_cndmask_b32_e64 v17, v39, v17, s[10:11]
	v_cndmask_b32_e64 v16, v38, v16, s[10:11]
	v_pk_fma_f32 v[8:9], v[8:9], v[88:89], v[92:93]
	v_pk_fma_f32 v[6:7], v[82:83], v[12:13], v[6:7]
	v_cndmask_b32_e64 v15, v41, v15, s[10:11]
	v_cndmask_b32_e64 v14, v40, v14, s[10:11]
	v_pk_fma_f32 v[8:9], v[84:85], v[10:11], v[8:9]
	v_pk_fma_f32 v[6:7], v[78:79], v[16:17], v[6:7]
	v_pk_fma_f32 v[8:9], v[80:81], v[14:15], v[8:9]
	v_mul_f32_e32 v10, v6, v6
	v_mul_f32_e32 v11, v7, v7
	v_fmamk_f32 v10, v10, 0xbdd2d3e8, v196
	v_fmamk_f32 v11, v11, 0xbdd2d3e8, v196
	v_mul_f32_e32 v12, v8, v8
	v_mul_f32_e32 v13, v9, v9
	v_mul_f32_e32 v10, v6, v10
	v_mul_f32_e32 v11, v7, v11
	v_fmamk_f32 v12, v12, 0xbdd2d3e8, v196
	v_fmamk_f32 v13, v13, 0xbdd2d3e8, v196
	v_exp_f32_e32 v10, v10
	v_exp_f32_e32 v11, v11
	v_mul_f32_e32 v12, v8, v12
	v_mul_f32_e32 v13, v9, v13
	v_exp_f32_e32 v12, v12
	v_exp_f32_e32 v13, v13
	v_add_f32_e32 v10, 1.0, v10
	v_add_f32_e32 v11, 1.0, v11
	v_pk_mul_f32 v[2:3], v[2:3], v[178:179]
	s_nop 0
	s_nop 0
	v_rcp_f32_e32 v10, v10
	v_add_f32_e32 v12, 1.0, v12
	v_add_f32_e32 v13, 1.0, v13
	v_rcp_f32_e32 v11, v11
	v_mov_b32_dpp v20, v2 row_ror:1 row_mask:0xf bank_mask:0xf
	v_mov_b32_dpp v21, v3 row_ror:1 row_mask:0xf bank_mask:0xf
	s_nop 0
	s_nop 0
	s_nop 0
	s_nop 0
	v_rcp_f32_e32 v12, v12
	v_rcp_f32_e32 v13, v13
	v_mov_b32_dpp v18, v4 row_ror:1 row_mask:0xf bank_mask:0xf
	v_mov_b32_dpp v19, v5 row_ror:1 row_mask:0xf bank_mask:0xf
	v_mov_b32_dpp v24, v2 row_ror:2 row_mask:0xf bank_mask:0xf
	v_mov_b32_dpp v25, v3 row_ror:2 row_mask:0xf bank_mask:0xf
	s_nop 0
	s_nop 0
	v_cndmask_b32_e64 v21, v21, v43, s[6:7]
	v_cndmask_b32_e64 v20, v20, v42, s[6:7]
	v_pk_fma_f32 v[2:3], v[2:3], v[70:71], v[94:95]
	v_mov_b32_dpp v22, v4 row_ror:2 row_mask:0xf bank_mask:0xf
	v_mov_b32_dpp v23, v5 row_ror:2 row_mask:0xf bank_mask:0xf
	v_cndmask_b32_e64 v19, v19, v45, s[6:7]
	v_cndmask_b32_e64 v18, v18, v44, s[6:7]
	v_cndmask_b32_e64 v25, v63, v25, s[10:11]
	v_cndmask_b32_e64 v24, v62, v24, s[10:11]
	v_pk_fma_f32 v[4:5], v[4:5], v[72:73], v[96:97]
	v_pk_fma_f32 v[2:3], v[74:75], v[20:21], v[2:3]
	v_cndmask_b32_e64 v23, v65, v23, s[10:11]
	v_cndmask_b32_e64 v22, v64, v22, s[10:11]
	v_pk_fma_f32 v[4:5], v[76:77], v[18:19], v[4:5]
	v_pk_fma_f32 v[2:3], v[66:67], v[24:25], v[2:3]
	v_pk_mul_f32 v[6:7], v[6:7], v[10:11]
	v_pk_fma_f32 v[4:5], v[68:69], v[22:23], v[4:5]
	v_pk_mul_f32 v[8:9], v[8:9], v[12:13]
	v_pk_mul_f32 v[2:3], v[2:3], v[6:7]
	s_andn2_b64 vcc, exec, s[8:9]
	s_mov_b64 s[8:9], -1
	v_pk_mul_f32 v[4:5], v[4:5], v[8:9]
	v_cvt_pk_bf16_f32 v2, v2, v3
	s_nop 0
	v_cvt_pk_bf16_f32 v3, v4, v5
	global_store_dwordx2 v[106:107], v[2:3], off offset:8
	s_cbranch_vccnz .LBB0_39
	s_andn2_b64 vcc, exec, s[2:3]
	s_cbranch_vccnz .LBB0_38
	s_barrier
	s_branch .LBB0_38
